# attention k-loop: far-tile path hand-interleaved (QK/softmax/PV), global prefetch in MFMA gaps, counted vmcnt, inline row sums
# speedup vs baseline: 1.0002x; 1.0002x over previous
.LBB0_583:
	s_waitcnt lgkmcnt(0)
	s_barrier
	s_add_i32 s47, s47, 2
	v_lshl_add_u64 v[190:191], v[190:191], 0, s[84:85]
	v_lshl_add_u64 v[192:193], v[192:193], 0, s[26:27]
	s_addk_i32 s22, 0x80
	s_and_b64 vcc, exec, s[0:1]
	s_cbranch_vccnz .LBB0_598

.LBB0_586:
	s_add_i32 s68, s46, s22
	s_setprio 1
	ds_read_b128 v[140:143], v247
	ds_read_b128 v[136:139], v247 offset:32
	ds_read_b128 v[132:135], v247 offset:64
	ds_read_b128 v[128:131], v247 offset:96
	ds_read_b128 v[172:175], v246
	ds_read_b128 v[168:171], v246 offset:32
	ds_read_b128 v[164:167], v246 offset:64
	ds_read_b128 v[160:163], v246 offset:96
	ds_read_b128 v[156:159], v246 offset:8704
	ds_read_b128 v[152:155], v246 offset:8736
	ds_read_b128 v[148:151], v246 offset:8768
	ds_read_b128 v[144:147], v246 offset:8800
	s_cmp_lt_u32 s22, s63
	s_cselect_b64 s[42:43], -1, 0
	s_cmpk_gt_i32 s68, 0xff41
	s_cselect_b64 s[70:71], -1, 0
	s_and_b64 s[70:71], s[42:43], s[70:71]
	s_and_b64 vcc, exec, s[70:71]
	s_cbranch_vccnz .LBB0_588
	s_and_b64 s[42:43], s[42:43], exec
	s_cselect_b32 s42, 0, 0x400
	s_add_i32 s42, s62, s42
	v_mov_b32_e32 v64, s42
	ds_read_b32 v225, v64
	v_add_u32_e32 v249, s22, v245
	s_cmp_eq_u64 s[40:41], 0
	s_waitcnt lgkmcnt(8)
	v_mfma_f32_32x32x16_bf16 v[64:79], v[172:175], v[140:143], 0
	s_cbranch_scc1 .La1t0_nl0
	v_add_co_u32_e32 v186, vcc, 0xfffe8000, v190
	s_nop 1
	v_addc_co_u32_e32 v187, vcc, -1, v191, vcc
	global_load_dwordx4 v[96:99], v[186:187], off
.La1t0_nl0:
	s_waitcnt lgkmcnt(7)
	v_mfma_f32_32x32x16_bf16 v[64:79], v[168:171], v[136:139], v[64:79]
	s_cbranch_scc1 .La1t0_nl1
	v_add_co_u32_e32 v186, vcc, 0xffff0000, v190
	s_nop 1
	v_addc_co_u32_e32 v187, vcc, -1, v191, vcc
	global_load_dwordx4 v[100:103], v[186:187], off
.La1t0_nl1:
	s_waitcnt lgkmcnt(6)
	v_mfma_f32_32x32x16_bf16 v[64:79], v[164:167], v[132:135], v[64:79]
	s_cbranch_scc1 .La1t0_nl2
	v_add_co_u32_e32 v186, vcc, 0xffbfff80, v192
	s_nop 1
	v_addc_co_u32_e32 v187, vcc, -1, v193, vcc
	global_load_dwordx4 v[120:123], v[186:187], off
.La1t0_nl2:
	s_waitcnt lgkmcnt(5)
	v_mfma_f32_32x32x16_bf16 v[64:79], v[160:163], v[128:131], v[64:79]
	s_cbranch_scc1 .La1t0_nl3
	v_add_co_u32_e32 v186, vcc, 0xffffff80, v192
	s_nop 1
	v_addc_co_u32_e32 v187, vcc, -1, v193, vcc
	global_load_dwordx4 v[124:127], v[186:187], off
.La1t0_nl3:
	s_waitcnt lgkmcnt(4)
	v_mfma_f32_32x32x16_bf16 v[80:95], v[156:159], v[140:143], 0
	s_waitcnt lgkmcnt(0)
	s_nop 10
	v_add_f32_e32 v64, v64, v225
	v_add_f32_e32 v65, v65, v225
	v_add_f32_e32 v66, v66, v225
	v_add_f32_e32 v67, v67, v225
	v_add_f32_e32 v68, v68, v225
	v_add_f32_e32 v69, v69, v225
	v_add_f32_e32 v70, v70, v225
	v_add_f32_e32 v71, v71, v225
	v_add_f32_e32 v72, v72, v225
	v_add_f32_e32 v73, v73, v225
	v_mfma_f32_32x32x16_bf16 v[80:95], v[152:155], v[136:139], v[80:95]
	v_add_f32_e32 v74, v74, v225
	v_add_f32_e32 v75, v75, v225
	v_add_f32_e32 v76, v76, v225
	v_add_f32_e32 v77, v77, v225
	v_add_f32_e32 v78, v78, v225
	v_add_f32_e32 v79, v79, v225
	v_exp_f32_e32 v194, v64
	v_exp_f32_e32 v195, v65
	v_exp_f32_e32 v196, v66
	v_exp_f32_e32 v197, v67
	v_mfma_f32_32x32x16_bf16 v[80:95], v[148:151], v[132:135], v[80:95]
	v_exp_f32_e32 v198, v68
	v_exp_f32_e32 v199, v69
	v_exp_f32_e32 v200, v70
	v_exp_f32_e32 v201, v71
	v_exp_f32_e32 v202, v72
	v_exp_f32_e32 v203, v73
	v_exp_f32_e32 v204, v74
	v_exp_f32_e32 v205, v75
	v_exp_f32_e32 v206, v76
	v_exp_f32_e32 v207, v77
	v_mfma_f32_32x32x16_bf16 v[80:95], v[144:147], v[128:131], v[80:95]
	ds_read_b128 v[144:147], v243 offset:34816
	ds_read_b128 v[148:151], v243 offset:34848
	ds_read_b128 v[152:155], v243 offset:39424
	ds_read_b128 v[156:159], v243 offset:39456
	ds_read_b128 v[128:131], v243 offset:44032
	ds_read_b128 v[132:135], v243 offset:44064
	ds_read_b128 v[136:139], v243 offset:48640
	ds_read_b128 v[140:143], v243 offset:48672
	v_exp_f32_e32 v208, v78
	v_exp_f32_e32 v209, v79
	v_cvt_pk_bf16_f32 v64, v194, v195
	v_cvt_pk_bf16_f32 v65, v196, v197
	v_cvt_pk_bf16_f32 v66, v198, v199
	v_cvt_pk_bf16_f32 v67, v200, v201
	v_cvt_pk_bf16_f32 v68, v202, v203
	v_cvt_pk_bf16_f32 v69, v204, v205
	v_cvt_pk_bf16_f32 v70, v206, v207
	v_cvt_pk_bf16_f32 v71, v208, v209
	v_add_f32_e32 v80, v80, v225
	v_add_f32_e32 v81, v81, v225
	v_add_f32_e32 v82, v82, v225
	v_add_f32_e32 v83, v83, v225
	v_add_f32_e32 v84, v84, v225
	v_add_f32_e32 v85, v85, v225
	v_add_f32_e32 v86, v86, v225
	v_add_f32_e32 v87, v87, v225
	v_add_f32_e32 v88, v88, v225
	v_add_f32_e32 v89, v89, v225
	s_waitcnt lgkmcnt(7)
	v_mfma_f32_32x32x16_bf16 v[48:63], v[144:147], v[64:67], v[48:63]
	s_cmp_eq_u64 s[40:41], 0
	s_cbranch_scc1 .La1t0_lv_a
	s_waitcnt vmcnt(4)
	s_branch .La1t0_lv_b

.La1t0_lv_b:
	v_add_u32_e32 v251, 0xd000, v240
	ds_write_b128 v239, v[104:107] offset:17408
	ds_write_b128 v239, v[108:111] offset:26112
	ds_write2_b64 v251, v[112:113], v[114:115] offset1:2
	v_add_u32_e32 v251, 0xf000, v240
	ds_write2_b64 v251, v[116:117], v[118:119] offset0:128 offset1:130
	v_add_f32_e32 v90, v90, v225
	v_add_f32_e32 v91, v91, v225
	v_add_f32_e32 v92, v92, v225
	v_add_f32_e32 v93, v93, v225
	s_waitcnt lgkmcnt(6)
	v_mfma_f32_32x32x16_bf16 v[48:63], v[148:151], v[68:71], v[48:63]
	ds_read_b128 v[144:147], v243 offset:34880
	ds_read_b128 v[148:151], v243 offset:34912
	v_add_f32_e32 v94, v94, v225
	v_add_f32_e32 v95, v95, v225
	v_exp_f32_e32 v210, v80
	v_exp_f32_e32 v211, v81
	s_waitcnt lgkmcnt(7)
	v_mfma_f32_32x32x16_bf16 v[32:47], v[152:155], v[64:67], v[32:47]
	v_exp_f32_e32 v212, v82
	v_exp_f32_e32 v213, v83
	v_exp_f32_e32 v214, v84
	v_exp_f32_e32 v215, v85
	s_waitcnt lgkmcnt(6)
	v_mfma_f32_32x32x16_bf16 v[32:47], v[156:159], v[68:71], v[32:47]
	ds_read_b128 v[152:155], v243 offset:39488
	ds_read_b128 v[156:159], v243 offset:39520
	v_exp_f32_e32 v216, v86
	v_exp_f32_e32 v217, v87
	v_exp_f32_e32 v218, v88
	v_exp_f32_e32 v219, v89
	s_waitcnt lgkmcnt(7)
	v_mfma_f32_32x32x16_bf16 v[16:31], v[128:131], v[64:67], v[16:31]
	v_exp_f32_e32 v220, v90
	v_exp_f32_e32 v221, v91
	v_exp_f32_e32 v222, v92
	v_exp_f32_e32 v223, v93
	s_waitcnt lgkmcnt(6)
	v_mfma_f32_32x32x16_bf16 v[16:31], v[132:135], v[68:71], v[16:31]
	ds_read_b128 v[128:131], v243 offset:44096
	ds_read_b128 v[132:135], v243 offset:44128
	v_exp_f32_e32 v224, v94
	v_exp_f32_e32 v225, v95
	v_cvt_pk_bf16_f32 v72, v210, v211
	v_cvt_pk_bf16_f32 v73, v212, v213
	s_waitcnt lgkmcnt(7)
	v_mfma_f32_32x32x16_bf16 v[0:15], v[136:139], v[64:67], v[0:15]
	v_cvt_pk_bf16_f32 v74, v214, v215
	v_cvt_pk_bf16_f32 v75, v216, v217
	v_cvt_pk_bf16_f32 v76, v218, v219
	s_waitcnt lgkmcnt(6)
	v_mfma_f32_32x32x16_bf16 v[0:15], v[140:143], v[68:71], v[0:15]
	ds_read_b128 v[136:139], v243 offset:48704
	ds_read_b128 v[140:143], v243 offset:48736
	v_cvt_pk_bf16_f32 v77, v220, v221
	v_cvt_pk_bf16_f32 v78, v222, v223
	v_cvt_pk_bf16_f32 v79, v224, v225
	s_nop 1
	s_waitcnt lgkmcnt(7)
	v_mfma_f32_32x32x16_bf16 v[48:63], v[144:147], v[72:75], v[48:63]
	v_add_f32_e32 v80, v194, v198
	v_add_f32_e32 v81, v195, v199
	v_add_f32_e32 v82, v196, v200
	v_add_f32_e32 v83, v197, v201
	s_waitcnt lgkmcnt(6)
	v_mfma_f32_32x32x16_bf16 v[48:63], v[148:151], v[76:79], v[48:63]
	v_add_f32_e32 v80, v80, v202
	v_add_f32_e32 v81, v81, v203
	v_add_f32_e32 v82, v82, v204
	v_add_f32_e32 v83, v83, v205
	s_waitcnt lgkmcnt(5)
	v_mfma_f32_32x32x16_bf16 v[32:47], v[152:155], v[72:75], v[32:47]
	v_add_f32_e32 v80, v80, v206
	v_add_f32_e32 v81, v81, v207
	v_add_f32_e32 v82, v82, v208
	v_add_f32_e32 v83, v83, v209
	s_waitcnt lgkmcnt(4)
	v_mfma_f32_32x32x16_bf16 v[32:47], v[156:159], v[76:79], v[32:47]
	v_add_f32_e32 v80, v80, v210
	v_add_f32_e32 v81, v81, v211
	v_add_f32_e32 v82, v82, v212
	v_add_f32_e32 v83, v83, v213
	s_waitcnt lgkmcnt(3)
	v_mfma_f32_32x32x16_bf16 v[16:31], v[128:131], v[72:75], v[16:31]
	v_add_f32_e32 v80, v80, v214
	v_add_f32_e32 v81, v81, v215
	v_add_f32_e32 v82, v82, v216
	v_add_f32_e32 v83, v83, v217
	s_waitcnt lgkmcnt(2)
	v_mfma_f32_32x32x16_bf16 v[16:31], v[132:135], v[76:79], v[16:31]
	v_add_f32_e32 v80, v80, v218
	v_add_f32_e32 v81, v81, v219
	v_add_f32_e32 v82, v82, v220
	v_add_f32_e32 v83, v83, v221
	s_waitcnt lgkmcnt(1)
	v_mfma_f32_32x32x16_bf16 v[0:15], v[136:139], v[72:75], v[0:15]
	v_add_f32_e32 v80, v80, v222
	v_add_f32_e32 v81, v81, v223
	v_add_f32_e32 v82, v82, v224
	v_add_f32_e32 v83, v83, v225
	s_waitcnt lgkmcnt(0)
	v_mfma_f32_32x32x16_bf16 v[0:15], v[140:143], v[76:79], v[0:15]
	v_add_f32_e32 v80, v80, v81
	v_add_f32_e32 v82, v82, v83
	v_add_f32_e32 v80, v80, v82
	v_add_f32_e32 v248, v248, v80
	s_setprio 0
	s_branch .La1t0_pw
.LBB0_588:
	s_cmp_eq_u64 s[40:41], 0
	s_cbranch_scc1 .La1t0_nrl
	v_add_co_u32_e32 v64, vcc, 0xfffe8000, v190
	s_nop 1
	v_addc_co_u32_e32 v65, vcc, -1, v191, vcc
	v_add_co_u32_e32 v66, vcc, 0xffff0000, v190
	s_nop 1
	v_addc_co_u32_e32 v67, vcc, -1, v191, vcc
	global_load_dwordx4 v[96:99], v[64:65], off
	global_load_dwordx4 v[100:103], v[66:67], off
	v_add_co_u32_e32 v64, vcc, 0xffbfff80, v192
	s_nop 1
	v_addc_co_u32_e32 v65, vcc, -1, v193, vcc
	v_add_co_u32_e32 v66, vcc, 0xffffff80, v192
	s_nop 1
	v_addc_co_u32_e32 v67, vcc, -1, v193, vcc
	global_load_dwordx4 v[120:123], v[64:65], off
	global_load_dwordx4 v[124:127], v[66:67], off

.LBB0_590:
	s_setprio 0
	s_waitcnt lgkmcnt(0)
	ds_read_b128 v[128:131], v243 offset:34816
	ds_read_b128 v[132:135], v243 offset:34848
	ds_read_b128 v[136:139], v243 offset:34880
	ds_read_b128 v[140:143], v243 offset:34912
	s_nop 1
	v_add_f32_e32 v64, v64, v225
	v_exp_f32_e32 v194, v64
	v_add_f32_e32 v64, v65, v225
	v_exp_f32_e32 v195, v64
	v_add_f32_e32 v64, v66, v225
	v_exp_f32_e32 v196, v64
	v_add_f32_e32 v64, v67, v225
	v_exp_f32_e32 v197, v64
	v_add_f32_e32 v64, v68, v225
	v_exp_f32_e32 v198, v64
	v_add_f32_e32 v64, v69, v225
	v_exp_f32_e32 v199, v64
	v_add_f32_e32 v64, v70, v225
	v_exp_f32_e32 v200, v64
	v_add_f32_e32 v64, v71, v225
	v_exp_f32_e32 v201, v64
	v_add_f32_e32 v64, v72, v225
	v_exp_f32_e32 v202, v64
	v_add_f32_e32 v64, v73, v225
	v_exp_f32_e32 v203, v64
	v_add_f32_e32 v64, v74, v225
	v_exp_f32_e32 v204, v64
	v_add_f32_e32 v64, v75, v225
	v_exp_f32_e32 v205, v64
	v_add_f32_e32 v64, v76, v225
	v_exp_f32_e32 v206, v64
	v_add_f32_e32 v64, v77, v225
	v_exp_f32_e32 v207, v64
	v_add_f32_e32 v64, v78, v225
	v_exp_f32_e32 v208, v64
	v_add_f32_e32 v64, v79, v225
	v_exp_f32_e32 v209, v64
	v_add_f32_e32 v64, v225, v80
	v_exp_f32_e32 v210, v64
	v_add_f32_e32 v64, v225, v81
	v_exp_f32_e32 v211, v64
	v_add_f32_e32 v64, v225, v82
	v_exp_f32_e32 v212, v64
	v_add_f32_e32 v64, v225, v83
	v_exp_f32_e32 v213, v64
	v_add_f32_e32 v64, v225, v84
	v_exp_f32_e32 v214, v64
	v_add_f32_e32 v64, v225, v85
	v_exp_f32_e32 v215, v64
	v_add_f32_e32 v64, v225, v86
	v_exp_f32_e32 v216, v64
	v_add_f32_e32 v64, v225, v87
	v_exp_f32_e32 v217, v64
	v_add_f32_e32 v64, v225, v88
	v_exp_f32_e32 v218, v64
	v_add_f32_e32 v64, v225, v89
	v_exp_f32_e32 v219, v64
	v_add_f32_e32 v64, v225, v90
	v_exp_f32_e32 v220, v64
	v_add_f32_e32 v64, v225, v91
	v_exp_f32_e32 v221, v64
	v_add_f32_e32 v64, v225, v92
	v_exp_f32_e32 v222, v64
	v_add_f32_e32 v64, v225, v93
	v_exp_f32_e32 v223, v64
	v_add_f32_e32 v64, v225, v94
	v_exp_f32_e32 v224, v64
	v_add_f32_e32 v64, v225, v95
	v_exp_f32_e32 v225, v64
	v_cvt_pk_bf16_f32 v64, v194, v195
	v_cvt_pk_bf16_f32 v65, v196, v197
	v_cvt_pk_bf16_f32 v66, v198, v199
	v_cvt_pk_bf16_f32 v67, v200, v201
	v_cvt_pk_bf16_f32 v68, v202, v203
	v_cvt_pk_bf16_f32 v69, v204, v205
	v_cvt_pk_bf16_f32 v70, v206, v207
	v_cvt_pk_bf16_f32 v71, v208, v209
	v_cvt_pk_bf16_f32 v72, v210, v211
	v_cvt_pk_bf16_f32 v73, v212, v213
	v_cvt_pk_bf16_f32 v74, v214, v215
	v_cvt_pk_bf16_f32 v75, v216, v217
	v_cvt_pk_bf16_f32 v76, v218, v219
	v_cvt_pk_bf16_f32 v77, v220, v221
	v_cvt_pk_bf16_f32 v78, v222, v223
	v_cvt_pk_bf16_f32 v79, v224, v225
	ds_read_b128 v[80:83], v243 offset:39424
	ds_read_b128 v[84:87], v243 offset:39456
	ds_read_b128 v[88:91], v243 offset:39488
	ds_read_b128 v[92:95], v243 offset:39520
	s_setprio 1
	s_waitcnt lgkmcnt(0)
	v_mfma_f32_32x32x16_bf16 v[48:63], v[128:131], v[64:67], v[48:63]
	v_mfma_f32_32x32x16_bf16 v[48:63], v[132:135], v[68:71], v[48:63]
	v_mfma_f32_32x32x16_bf16 v[48:63], v[136:139], v[72:75], v[48:63]
	v_mfma_f32_32x32x16_bf16 v[48:63], v[140:143], v[76:79], v[48:63]
	ds_read_b128 v[128:131], v243 offset:44032
	ds_read_b128 v[132:135], v243 offset:44064
	ds_read_b128 v[136:139], v243 offset:44096
	ds_read_b128 v[140:143], v243 offset:44128
	v_mfma_f32_32x32x16_bf16 v[32:47], v[80:83], v[64:67], v[32:47]
	v_mfma_f32_32x32x16_bf16 v[32:47], v[84:87], v[68:71], v[32:47]
	v_mfma_f32_32x32x16_bf16 v[32:47], v[88:91], v[72:75], v[32:47]
	v_mfma_f32_32x32x16_bf16 v[32:47], v[92:95], v[76:79], v[32:47]
	ds_read_b128 v[80:83], v243 offset:48640
	ds_read_b128 v[84:87], v243 offset:48672
	ds_read_b128 v[88:91], v243 offset:48704
	ds_read_b128 v[92:95], v243 offset:48736
	s_waitcnt lgkmcnt(0)
	v_mfma_f32_32x32x16_bf16 v[16:31], v[128:131], v[64:67], v[16:31]
	v_mfma_f32_32x32x16_bf16 v[0:15], v[80:83], v[64:67], v[0:15]
	v_mfma_f32_32x32x16_bf16 v[16:31], v[132:135], v[68:71], v[16:31]
	v_mfma_f32_32x32x16_bf16 v[0:15], v[84:87], v[68:71], v[0:15]
	v_mfma_f32_32x32x16_bf16 v[16:31], v[136:139], v[72:75], v[16:31]
	v_mfma_f32_32x32x16_bf16 v[0:15], v[88:91], v[72:75], v[0:15]
	v_mfma_f32_32x32x16_bf16 v[16:31], v[140:143], v[76:79], v[16:31]
	v_mfma_f32_32x32x16_bf16 v[0:15], v[92:95], v[76:79], v[0:15]
	s_setprio 0
	v_add_f32_e32 v128, v194, v198
	v_add_f32_e32 v129, v195, v199
	v_add_f32_e32 v130, v196, v200
	v_add_f32_e32 v131, v197, v201
	v_add_f32_e32 v128, v128, v202
	v_add_f32_e32 v129, v129, v203
	v_add_f32_e32 v130, v130, v204
	v_add_f32_e32 v131, v131, v205
	v_add_f32_e32 v128, v128, v206
	v_add_f32_e32 v129, v129, v207
	v_add_f32_e32 v130, v130, v208
	v_add_f32_e32 v131, v131, v209
	v_add_f32_e32 v128, v128, v210
	v_add_f32_e32 v129, v129, v211
	v_add_f32_e32 v130, v130, v212
	v_add_f32_e32 v131, v131, v213
	v_add_f32_e32 v128, v128, v214
	v_add_f32_e32 v129, v129, v215
	v_add_f32_e32 v130, v130, v216
	v_add_f32_e32 v131, v131, v217
	v_add_f32_e32 v128, v128, v218
	v_add_f32_e32 v129, v129, v219
	v_add_f32_e32 v130, v130, v220
	v_add_f32_e32 v131, v131, v221
	v_add_f32_e32 v128, v128, v222
	v_add_f32_e32 v129, v129, v223
	v_add_f32_e32 v130, v130, v224
	v_add_f32_e32 v131, v131, v225
	v_add_f32_e32 v128, v128, v129
	v_add_f32_e32 v130, v130, v131
	v_add_f32_e32 v128, v128, v130
	v_add_f32_e32 v248, v248, v128
	v_add_u32_e32 v64, 0xd000, v240
	s_cmp_eq_u64 s[40:41], 0
	s_cbranch_scc1 .La1_n0v_a
	s_waitcnt vmcnt(4)
	s_branch .La1_n0v_b

.La1_n0v_b:
	ds_write_b128 v239, v[104:107] offset:17408
	ds_write_b128 v239, v[108:111] offset:26112
	ds_write2_b64 v64, v[112:113], v[114:115] offset1:2
	v_add_u32_e32 v64, 0xf000, v240
	ds_write2_b64 v64, v[116:117], v[118:119] offset0:128 offset1:130
.La1t0_pw:
	s_waitcnt lgkmcnt(0)
	s_barrier
	s_cmp_gt_u32 s47, 28
	s_cbranch_scc1 .LBB0_592
.LBB0_592:
	s_setprio 1
	ds_read_b128 v[140:143], v247
	ds_read_b128 v[136:139], v247 offset:32
	ds_read_b128 v[132:135], v247 offset:64
	ds_read_b128 v[128:131], v247 offset:96
	ds_read_b128 v[172:175], v246 offset:17408
	ds_read_b128 v[168:171], v246 offset:17440
	ds_read_b128 v[164:167], v246 offset:17472
	ds_read_b128 v[160:163], v246 offset:17504
	ds_read_b128 v[156:159], v246 offset:26112
	ds_read_b128 v[152:155], v246 offset:26144
	ds_read_b128 v[148:151], v246 offset:26176
	ds_read_b128 v[144:147], v246 offset:26208
	s_cmp_lt_u32 s22, s72
	s_cselect_b64 s[42:43], -1, 0
	s_cmpk_gt_i32 s68, 0xff01
	s_cselect_b64 s[68:69], -1, 0
	s_and_b64 s[68:69], s[42:43], s[68:69]
	s_and_b64 vcc, exec, s[68:69]
	s_cbranch_vccnz .LBB0_594
	s_and_b64 s[42:43], s[42:43], exec
	s_cselect_b32 s42, 0, 0x400
	s_add_i32 s42, s62, s42
	v_mov_b32_e32 v64, s42
	ds_read_b32 v250, v64
	s_cmp_eq_u64 s[40:41], 0
	s_waitcnt lgkmcnt(8)
	v_mfma_f32_32x32x16_bf16 v[64:79], v[172:175], v[140:143], 0
	s_cbranch_scc1 .La1t1_nl0
	v_add_co_u32_e32 v186, vcc, 0xffff8000, v190
	s_nop 1
	v_addc_co_u32_e32 v187, vcc, -1, v191, vcc
	global_load_dwordx4 v[104:107], v[186:187], off
.La1t1_nl0:
	s_waitcnt lgkmcnt(7)
	v_mfma_f32_32x32x16_bf16 v[64:79], v[168:171], v[136:139], v[64:79]
	s_cbranch_scc1 .La1t1_nl1
	global_load_dwordx4 v[108:111], v[190:191], off
.La1t1_nl1:
	s_waitcnt lgkmcnt(6)
	v_mfma_f32_32x32x16_bf16 v[64:79], v[164:167], v[132:135], v[64:79]
	s_cbranch_scc1 .La1t1_nl2
	v_add_co_u32_e32 v186, vcc, 0xffc00000, v192
	s_nop 1
	v_addc_co_u32_e32 v187, vcc, -1, v193, vcc
	global_load_dwordx4 v[112:115], v[186:187], off
.La1t1_nl2:
	s_waitcnt lgkmcnt(5)
	v_mfma_f32_32x32x16_bf16 v[64:79], v[160:163], v[128:131], v[64:79]
	s_cbranch_scc1 .La1t1_nl3
	global_load_dwordx4 v[116:119], v[192:193], off
.La1t1_nl3:
	s_waitcnt lgkmcnt(4)
	v_mfma_f32_32x32x16_bf16 v[80:95], v[156:159], v[140:143], 0
	s_waitcnt lgkmcnt(0)
	s_nop 10
	v_add_f32_e32 v64, v64, v250
	v_add_f32_e32 v65, v65, v250
	v_add_f32_e32 v66, v66, v250
	v_add_f32_e32 v67, v67, v250
	v_add_f32_e32 v68, v68, v250
	v_add_f32_e32 v69, v69, v250
	v_add_f32_e32 v70, v70, v250
	v_add_f32_e32 v71, v71, v250
	v_add_f32_e32 v72, v72, v250
	v_add_f32_e32 v73, v73, v250
	v_mfma_f32_32x32x16_bf16 v[80:95], v[152:155], v[136:139], v[80:95]
	v_add_f32_e32 v74, v74, v250
	v_add_f32_e32 v75, v75, v250
	v_add_f32_e32 v76, v76, v250
	v_add_f32_e32 v77, v77, v250
	v_add_f32_e32 v78, v78, v250
	v_add_f32_e32 v79, v79, v250
	v_exp_f32_e32 v64, v64
	v_exp_f32_e32 v65, v65
	v_exp_f32_e32 v66, v66
	v_exp_f32_e32 v67, v67
	v_mfma_f32_32x32x16_bf16 v[80:95], v[148:151], v[132:135], v[80:95]
	v_exp_f32_e32 v68, v68
	v_exp_f32_e32 v69, v69
	v_exp_f32_e32 v70, v70
	v_exp_f32_e32 v71, v71
	v_exp_f32_e32 v72, v72
	v_exp_f32_e32 v73, v73
	v_exp_f32_e32 v74, v74
	v_exp_f32_e32 v75, v75
	v_exp_f32_e32 v76, v76
	v_exp_f32_e32 v77, v77
	v_mfma_f32_32x32x16_bf16 v[80:95], v[144:147], v[128:131], v[80:95]
	ds_read_b128 v[144:147], v243 offset:53248
	ds_read_b128 v[148:151], v243 offset:53280
	ds_read_b128 v[152:155], v243 offset:57856
	ds_read_b128 v[156:159], v243 offset:57888
	ds_read_b128 v[128:131], v243 offset:62464
	ds_read_b128 v[132:135], v243 offset:62496
	ds_read_b128 v[136:139], v244 offset:13824
	ds_read_b128 v[140:143], v244 offset:13856
	v_exp_f32_e32 v78, v78
	v_exp_f32_e32 v79, v79
	v_cvt_pk_bf16_f32 v160, v64, v65
	v_cvt_pk_bf16_f32 v161, v66, v67
	v_cvt_pk_bf16_f32 v162, v68, v69
	v_cvt_pk_bf16_f32 v163, v70, v71
	v_cvt_pk_bf16_f32 v164, v72, v73
	v_cvt_pk_bf16_f32 v165, v74, v75
	v_cvt_pk_bf16_f32 v166, v76, v77
	v_cvt_pk_bf16_f32 v167, v78, v79
	v_add_f32_e32 v80, v80, v250
	v_add_f32_e32 v81, v81, v250
	v_add_f32_e32 v82, v82, v250
	v_add_f32_e32 v83, v83, v250
	v_add_f32_e32 v84, v84, v250
	v_add_f32_e32 v85, v85, v250
	v_add_f32_e32 v86, v86, v250
	v_add_f32_e32 v87, v87, v250
	v_add_f32_e32 v88, v88, v250
	v_add_f32_e32 v89, v89, v250
	s_waitcnt lgkmcnt(7)
	v_mfma_f32_32x32x16_bf16 v[48:63], v[144:147], v[160:163], v[48:63]
	s_cmp_eq_u64 s[40:41], 0
	s_cbranch_scc1 .La1t1_lv_s
	s_waitcnt vmcnt(4)
	ds_write_b128 v239, v[96:99]
	ds_write_b128 v239, v[100:103] offset:8704
	ds_write2_b64 v241, v[120:121], v[122:123] offset1:2
	ds_write2_b64 v242, v[124:125], v[126:127] offset0:128 offset1:130
.La1t1_lv_s:
	v_add_f32_e32 v90, v90, v250
	v_add_f32_e32 v91, v91, v250
	v_add_f32_e32 v92, v92, v250
	v_add_f32_e32 v93, v93, v250
	s_waitcnt lgkmcnt(6)
	v_mfma_f32_32x32x16_bf16 v[48:63], v[148:151], v[164:167], v[48:63]
	ds_read_b128 v[144:147], v243 offset:53312
	ds_read_b128 v[148:151], v243 offset:53344
	v_add_f32_e32 v94, v94, v250
	v_add_f32_e32 v95, v95, v250
	v_exp_f32_e32 v80, v80
	v_exp_f32_e32 v81, v81
	s_waitcnt lgkmcnt(7)
	v_mfma_f32_32x32x16_bf16 v[32:47], v[152:155], v[160:163], v[32:47]
	v_exp_f32_e32 v82, v82
	v_exp_f32_e32 v83, v83
	v_exp_f32_e32 v84, v84
	v_exp_f32_e32 v85, v85
	s_waitcnt lgkmcnt(6)
	v_mfma_f32_32x32x16_bf16 v[32:47], v[156:159], v[164:167], v[32:47]
	ds_read_b128 v[152:155], v243 offset:57920
	ds_read_b128 v[156:159], v243 offset:57952
	v_exp_f32_e32 v86, v86
	v_exp_f32_e32 v87, v87
	v_exp_f32_e32 v88, v88
	v_exp_f32_e32 v89, v89
	s_waitcnt lgkmcnt(7)
	v_mfma_f32_32x32x16_bf16 v[16:31], v[128:131], v[160:163], v[16:31]
	v_exp_f32_e32 v90, v90
	v_exp_f32_e32 v91, v91
	v_exp_f32_e32 v92, v92
	v_exp_f32_e32 v93, v93
	s_waitcnt lgkmcnt(6)
	v_mfma_f32_32x32x16_bf16 v[16:31], v[132:135], v[164:167], v[16:31]
	ds_read_b128 v[128:131], v243 offset:62528
	ds_read_b128 v[132:135], v243 offset:62560
	v_exp_f32_e32 v94, v94
	v_exp_f32_e32 v95, v95
	v_cvt_pk_bf16_f32 v168, v80, v81
	v_cvt_pk_bf16_f32 v169, v82, v83
	s_waitcnt lgkmcnt(7)
	v_mfma_f32_32x32x16_bf16 v[0:15], v[136:139], v[160:163], v[0:15]
	v_cvt_pk_bf16_f32 v170, v84, v85
	v_cvt_pk_bf16_f32 v171, v86, v87
	v_cvt_pk_bf16_f32 v172, v88, v89
	s_waitcnt lgkmcnt(6)
	v_mfma_f32_32x32x16_bf16 v[0:15], v[140:143], v[164:167], v[0:15]
	ds_read_b128 v[136:139], v244 offset:13888
	ds_read_b128 v[140:143], v244 offset:13920
	v_cvt_pk_bf16_f32 v173, v90, v91
	v_cvt_pk_bf16_f32 v174, v92, v93
	v_cvt_pk_bf16_f32 v175, v94, v95
	s_nop 1
	s_waitcnt lgkmcnt(7)
	v_mfma_f32_32x32x16_bf16 v[48:63], v[144:147], v[168:171], v[48:63]
	v_add_f32_e32 v194, v64, v68
	v_add_f32_e32 v195, v65, v69
	v_add_f32_e32 v196, v66, v70
	v_add_f32_e32 v197, v67, v71
	s_waitcnt lgkmcnt(6)
	v_mfma_f32_32x32x16_bf16 v[48:63], v[148:151], v[172:175], v[48:63]
	v_add_f32_e32 v194, v194, v72
	v_add_f32_e32 v195, v195, v73
	v_add_f32_e32 v196, v196, v74
	v_add_f32_e32 v197, v197, v75
	s_waitcnt lgkmcnt(5)
	v_mfma_f32_32x32x16_bf16 v[32:47], v[152:155], v[168:171], v[32:47]
	v_add_f32_e32 v194, v194, v76
	v_add_f32_e32 v195, v195, v77
	v_add_f32_e32 v196, v196, v78
	v_add_f32_e32 v197, v197, v79
	s_waitcnt lgkmcnt(4)
	v_mfma_f32_32x32x16_bf16 v[32:47], v[156:159], v[172:175], v[32:47]
	v_add_f32_e32 v194, v194, v80
	v_add_f32_e32 v195, v195, v81
	v_add_f32_e32 v196, v196, v82
	v_add_f32_e32 v197, v197, v83
	s_waitcnt lgkmcnt(3)
	v_mfma_f32_32x32x16_bf16 v[16:31], v[128:131], v[168:171], v[16:31]
	v_add_f32_e32 v194, v194, v84
	v_add_f32_e32 v195, v195, v85
	v_add_f32_e32 v196, v196, v86
	v_add_f32_e32 v197, v197, v87
	s_waitcnt lgkmcnt(2)
	v_mfma_f32_32x32x16_bf16 v[16:31], v[132:135], v[172:175], v[16:31]
	v_add_f32_e32 v194, v194, v88
	v_add_f32_e32 v195, v195, v89
	v_add_f32_e32 v196, v196, v90
	v_add_f32_e32 v197, v197, v91
	s_waitcnt lgkmcnt(1)
	v_mfma_f32_32x32x16_bf16 v[0:15], v[136:139], v[168:171], v[0:15]
	v_add_f32_e32 v194, v194, v92
	v_add_f32_e32 v195, v195, v93
	v_add_f32_e32 v196, v196, v94
	v_add_f32_e32 v197, v197, v95
	s_waitcnt lgkmcnt(0)
	v_mfma_f32_32x32x16_bf16 v[0:15], v[140:143], v[172:175], v[0:15]
	v_add_f32_e32 v194, v194, v195
	v_add_f32_e32 v196, v196, v197
	v_add_f32_e32 v194, v194, v196
	v_add_f32_e32 v248, v248, v194
	s_setprio 0
	s_branch .LBB0_583
.LBB0_594:
	s_cmp_eq_u64 s[40:41], 0
	s_cbranch_scc1 .La1t1_nrl
	v_add_co_u32_e32 v64, vcc, 0xffff8000, v190
	s_nop 1
	v_addc_co_u32_e32 v65, vcc, -1, v191, vcc
	global_load_dwordx4 v[104:107], v[64:65], off
	global_load_dwordx4 v[108:111], v[190:191], off
	v_add_co_u32_e32 v64, vcc, 0xffc00000, v192
	s_nop 1
	v_addc_co_u32_e32 v65, vcc, -1, v193, vcc
	global_load_dwordx4 v[112:115], v[64:65], off
	global_load_dwordx4 v[116:119], v[192:193], off

.LBB0_596:
	s_setprio 0
	s_waitcnt lgkmcnt(0)
	ds_read_b128 v[128:131], v243 offset:53248
	ds_read_b128 v[132:135], v243 offset:53280
	ds_read_b128 v[136:139], v243 offset:53312
	ds_read_b128 v[140:143], v243 offset:53344
	s_nop 2
	v_add_f32_e32 v64, v250, v64
	v_add_f32_e32 v65, v250, v65
	v_add_f32_e32 v66, v250, v66
	v_add_f32_e32 v67, v250, v67
	v_add_f32_e32 v68, v250, v68
	v_add_f32_e32 v69, v250, v69
	v_add_f32_e32 v70, v250, v70
	v_add_f32_e32 v71, v250, v71
	v_add_f32_e32 v72, v250, v72
	v_add_f32_e32 v73, v250, v73
	v_add_f32_e32 v74, v250, v74
	v_add_f32_e32 v75, v250, v75
	v_add_f32_e32 v76, v250, v76
	v_add_f32_e32 v77, v250, v77
	v_add_f32_e32 v78, v250, v78
	v_add_f32_e32 v79, v250, v79
	v_add_f32_e32 v80, v80, v250
	v_add_f32_e32 v81, v81, v250
	v_add_f32_e32 v82, v82, v250
	v_add_f32_e32 v83, v83, v250
	v_add_f32_e32 v84, v84, v250
	v_add_f32_e32 v85, v85, v250
	v_add_f32_e32 v86, v86, v250
	v_add_f32_e32 v87, v87, v250
	v_add_f32_e32 v88, v88, v250
	v_add_f32_e32 v89, v89, v250
	v_add_f32_e32 v90, v90, v250
	v_add_f32_e32 v91, v91, v250
	v_add_f32_e32 v92, v92, v250
	v_add_f32_e32 v93, v93, v250
	v_add_f32_e32 v94, v94, v250
	v_add_f32_e32 v95, v95, v250
	v_exp_f32_e32 v64, v64
	v_exp_f32_e32 v65, v65
	v_exp_f32_e32 v66, v66
	v_exp_f32_e32 v67, v67
	v_exp_f32_e32 v68, v68
	v_exp_f32_e32 v69, v69
	v_exp_f32_e32 v70, v70
	v_exp_f32_e32 v71, v71
	v_exp_f32_e32 v72, v72
	v_exp_f32_e32 v73, v73
	v_exp_f32_e32 v74, v74
	v_exp_f32_e32 v75, v75
	v_exp_f32_e32 v76, v76
	v_exp_f32_e32 v77, v77
	v_exp_f32_e32 v78, v78
	v_exp_f32_e32 v79, v79
	v_exp_f32_e32 v80, v80
	v_exp_f32_e32 v81, v81
	v_exp_f32_e32 v82, v82
	v_exp_f32_e32 v83, v83
	v_exp_f32_e32 v84, v84
	v_exp_f32_e32 v85, v85
	v_exp_f32_e32 v86, v86
	v_exp_f32_e32 v87, v87
	v_exp_f32_e32 v88, v88
	v_exp_f32_e32 v89, v89
	v_exp_f32_e32 v90, v90
	v_exp_f32_e32 v91, v91
	v_exp_f32_e32 v92, v92
	v_exp_f32_e32 v93, v93
	v_exp_f32_e32 v94, v94
	v_exp_f32_e32 v95, v95
	v_cvt_pk_bf16_f32 v144, v64, v65
	v_cvt_pk_bf16_f32 v145, v66, v67
	v_cvt_pk_bf16_f32 v146, v68, v69
	v_cvt_pk_bf16_f32 v147, v70, v71
	v_cvt_pk_bf16_f32 v148, v72, v73
	v_cvt_pk_bf16_f32 v149, v74, v75
	v_cvt_pk_bf16_f32 v150, v76, v77
	v_cvt_pk_bf16_f32 v151, v78, v79
	v_cvt_pk_bf16_f32 v152, v80, v81
	v_cvt_pk_bf16_f32 v153, v82, v83
	v_cvt_pk_bf16_f32 v154, v84, v85
	v_cvt_pk_bf16_f32 v155, v86, v87
	v_cvt_pk_bf16_f32 v156, v88, v89
	v_cvt_pk_bf16_f32 v157, v90, v91
	v_cvt_pk_bf16_f32 v158, v92, v93
	v_cvt_pk_bf16_f32 v159, v94, v95
	ds_read_b128 v[160:163], v243 offset:57856
	ds_read_b128 v[164:167], v243 offset:57888
	ds_read_b128 v[168:171], v243 offset:57920
	ds_read_b128 v[172:175], v243 offset:57952
	s_setprio 1
	s_waitcnt lgkmcnt(0)
	v_mfma_f32_32x32x16_bf16 v[48:63], v[128:131], v[144:147], v[48:63]
	v_mfma_f32_32x32x16_bf16 v[48:63], v[132:135], v[148:151], v[48:63]
	v_mfma_f32_32x32x16_bf16 v[48:63], v[136:139], v[152:155], v[48:63]
	v_mfma_f32_32x32x16_bf16 v[48:63], v[140:143], v[156:159], v[48:63]
	ds_read_b128 v[128:131], v243 offset:62464
	ds_read_b128 v[132:135], v243 offset:62496
	ds_read_b128 v[136:139], v243 offset:62528
	ds_read_b128 v[140:143], v243 offset:62560
	v_mfma_f32_32x32x16_bf16 v[32:47], v[160:163], v[144:147], v[32:47]
	v_mfma_f32_32x32x16_bf16 v[32:47], v[164:167], v[148:151], v[32:47]
	v_mfma_f32_32x32x16_bf16 v[32:47], v[168:171], v[152:155], v[32:47]
	v_mfma_f32_32x32x16_bf16 v[32:47], v[172:175], v[156:159], v[32:47]
	ds_read_b128 v[160:163], v244 offset:13824
	ds_read_b128 v[164:167], v244 offset:13856
	ds_read_b128 v[168:171], v244 offset:13888
	ds_read_b128 v[172:175], v244 offset:13920
	s_waitcnt lgkmcnt(0)
	v_mfma_f32_32x32x16_bf16 v[16:31], v[128:131], v[144:147], v[16:31]
	v_mfma_f32_32x32x16_bf16 v[0:15], v[160:163], v[144:147], v[0:15]
	v_mfma_f32_32x32x16_bf16 v[16:31], v[132:135], v[148:151], v[16:31]
	v_mfma_f32_32x32x16_bf16 v[0:15], v[164:167], v[148:151], v[0:15]
	v_mfma_f32_32x32x16_bf16 v[16:31], v[136:139], v[152:155], v[16:31]
	v_mfma_f32_32x32x16_bf16 v[0:15], v[168:171], v[152:155], v[0:15]
	v_mfma_f32_32x32x16_bf16 v[16:31], v[140:143], v[156:159], v[16:31]
	v_mfma_f32_32x32x16_bf16 v[0:15], v[172:175], v[156:159], v[0:15]
	s_setprio 0
	v_add_f32_e32 v128, v64, v68
	v_add_f32_e32 v129, v65, v69
	v_add_f32_e32 v130, v66, v70
	v_add_f32_e32 v131, v67, v71
	v_add_f32_e32 v128, v128, v72
	v_add_f32_e32 v129, v129, v73
	v_add_f32_e32 v130, v130, v74
	v_add_f32_e32 v131, v131, v75
	v_add_f32_e32 v128, v128, v76
	v_add_f32_e32 v129, v129, v77
	v_add_f32_e32 v130, v130, v78
	v_add_f32_e32 v131, v131, v79
	v_add_f32_e32 v128, v128, v80
	v_add_f32_e32 v129, v129, v81
	v_add_f32_e32 v130, v130, v82
	v_add_f32_e32 v131, v131, v83
	v_add_f32_e32 v128, v128, v84
	v_add_f32_e32 v129, v129, v85
	v_add_f32_e32 v130, v130, v86
	v_add_f32_e32 v131, v131, v87
	v_add_f32_e32 v128, v128, v88
	v_add_f32_e32 v129, v129, v89
	v_add_f32_e32 v130, v130, v90
	v_add_f32_e32 v131, v131, v91
	v_add_f32_e32 v128, v128, v92
	v_add_f32_e32 v129, v129, v93
	v_add_f32_e32 v130, v130, v94
	v_add_f32_e32 v131, v131, v95
	v_add_f32_e32 v128, v128, v129
	v_add_f32_e32 v130, v130, v131
	v_add_f32_e32 v128, v128, v130
	v_add_f32_e32 v248, v248, v128
	s_andn2_b64 vcc, exec, s[40:41]
	s_cbranch_vccnz .LBB0_583
	s_waitcnt vmcnt(4)
	ds_write_b128 v239, v[96:99]
	ds_write_b128 v239, v[100:103] offset:8704
	ds_write2_b64 v241, v[120:121], v[122:123] offset1:2
	ds_write2_b64 v242, v[124:125], v[126:127] offset0:128 offset1:130
	s_branch .LBB0_583

.LBB0_610:
	s_lshl_b32 s34, s52, 12
	s_or_b32 s34, s34, s58
	s_addk_i32 s34, 0x4000
	s_mov_b32 s35, s53
	s_lshl_b64 s[34:35], s[34:35], 11
	s_add_u32 s34, s36, s34
	s_addc_u32 s35, s37, s35
	s_lshl_b32 s36, s3, 1
	s_add_u32 s34, s34, s36
	s_addc_u32 s35, s35, 0
	s_add_u32 s34, s34, 0x4b00400
	s_addc_u32 s35, s35, 0
	s_lshl_b32 s52, s52, 9
	s_lshl_b64 s[36:37], s[52:53], 2
	s_add_u32 s0, s0, s36
	s_addc_u32 s1, s1, s37
	s_lshl_b32 s3, s3, 2
	v_or_b32_e32 v160, s71, v129
	s_add_u32 s0, s0, s3
	s_addc_u32 s1, s1, 0
	v_lshlrev_b32_e32 v176, 2, v160
	v_lshl_add_u64 v[130:131], s[0:1], 0, v[176:177]
	s_mov_b64 s[0:1], 0x34000
	v_lshl_add_u64 v[132:133], v[130:131], 0, s[0:1]
	s_mov_b32 s0, 0x34000
	v_add_co_u32_e32 v130, vcc, s0, v130
	v_ashrrev_i32_e32 v129, 31, v128
	s_nop 0
	v_addc_co_u32_e32 v131, vcc, 0, v131, vcc
	global_load_dwordx4 v[134:137], v[130:131], off
	global_load_dwordx4 v[142:145], v[132:133], off offset:16
	global_load_dwordx4 v[152:155], v[132:133], off offset:512
	global_load_dwordx4 v[156:159], v[132:133], off offset:528
	v_and_b32_e32 v130, 1, v140
	v_cmp_eq_u32_e32 vcc, 0, v130
	v_or_b32_e32 v146, 48, v128
	v_or_b32_e32 v148, 32, v128
	v_or_b32_e32 v150, 16, v128
	v_lshlrev_b64 v[128:129], 11, v[128:129]
	v_lshl_add_u64 v[128:129], s[34:35], 0, v[128:129]
	v_lshlrev_b32_e32 v176, 1, v160
	v_lshl_add_u64 v[128:129], v[128:129], 0, v[176:177]
	v_ashrrev_i32_e32 v151, 31, v150
	v_ashrrev_i32_e32 v149, 31, v148
	v_ashrrev_i32_e32 v147, 31, v146
	s_mov_b64 s[0:1], 0x40000
	v_readlane_b32 s11, v255, 22
	s_movk_i32 s12, 0x110
	s_waitcnt vmcnt(0) lgkmcnt(0)
	v_xor_b32_e32 v140, 0x80000000, v142
	v_xor_b32_e32 v141, 0x80000000, v143
	v_xor_b32_e32 v138, 0x80000000, v144
	v_xor_b32_e32 v139, 0x80000000, v145
	v_cndmask_b32_e32 v139, v139, v145, vcc
	v_cndmask_b32_e32 v138, v138, v144, vcc
	v_cndmask_b32_e32 v141, v141, v143, vcc
	v_cndmask_b32_e32 v140, v140, v142, vcc
	v_xor_b32_e32 v144, 0x80000000, v134
	v_xor_b32_e32 v145, 0x80000000, v135
	v_xor_b32_e32 v142, 0x80000000, v136
	v_xor_b32_e32 v143, 0x80000000, v137
	v_cndmask_b32_e32 v143, v143, v137, vcc
	v_cndmask_b32_e32 v142, v142, v136, vcc
	v_cndmask_b32_e32 v145, v145, v135, vcc
	v_cndmask_b32_e32 v144, v144, v134, vcc
	v_xor_b32_e32 v132, 0x80000000, v152
	v_xor_b32_e32 v133, 0x80000000, v153
	v_xor_b32_e32 v130, 0x80000000, v154
	v_xor_b32_e32 v131, 0x80000000, v155
	v_xor_b32_e32 v136, 0x80000000, v156
	v_xor_b32_e32 v137, 0x80000000, v157
	v_xor_b32_e32 v134, 0x80000000, v158
	v_xor_b32_e32 v135, 0x80000000, v159
	v_pk_add_f32 v[124:125], v[124:125], v[144:145]
	v_pk_add_f32 v[126:127], v[126:127], v[142:143]
	v_pk_add_f32 v[120:121], v[120:121], v[140:141]
	v_pk_add_f32 v[122:123], v[122:123], v[138:139]
	v_cndmask_b32_e32 v131, v131, v155, vcc
	v_cndmask_b32_e32 v130, v130, v154, vcc
	v_cndmask_b32_e32 v133, v133, v153, vcc
	v_cndmask_b32_e32 v132, v132, v152, vcc
	v_cndmask_b32_e32 v135, v135, v159, vcc
	v_cndmask_b32_e32 v134, v134, v158, vcc
	v_cndmask_b32_e32 v137, v137, v157, vcc
	v_cndmask_b32_e32 v136, v136, v156, vcc
	v_pk_mul_f32 v[126:127], v[126:127], s[56:57] op_sel_hi:[1,0]
	v_pk_mul_f32 v[124:125], v[124:125], s[56:57] op_sel_hi:[1,0]
	v_pk_mul_f32 v[152:153], v[122:123], s[56:57] op_sel_hi:[1,0]
	v_pk_mul_f32 v[122:123], v[120:121], s[56:57] op_sel_hi:[1,0]
	v_cvt_pk_bf16_f32 v120, v124, v125
	v_cvt_pk_bf16_f32 v121, v126, v127
	v_cvt_pk_bf16_f32 v122, v122, v123
	v_cvt_pk_bf16_f32 v123, v152, v153
	v_pk_add_f32 v[116:117], v[116:117], v[132:133]
	v_pk_add_f32 v[118:119], v[118:119], v[130:131]
	v_pk_add_f32 v[112:113], v[112:113], v[136:137]
	v_pk_add_f32 v[114:115], v[114:115], v[134:135]
	flat_store_dwordx4 v[128:129], v[120:123]
	v_pk_mul_f32 v[118:119], v[118:119], s[56:57] op_sel_hi:[1,0]
	v_pk_mul_f32 v[116:117], v[116:117], s[56:57] op_sel_hi:[1,0]
	v_pk_mul_f32 v[120:121], v[114:115], s[56:57] op_sel_hi:[1,0]
	v_pk_mul_f32 v[114:115], v[112:113], s[56:57] op_sel_hi:[1,0]
	v_cvt_pk_bf16_f32 v112, v116, v117
	v_cvt_pk_bf16_f32 v113, v118, v119
	v_cvt_pk_bf16_f32 v114, v114, v115
	v_cvt_pk_bf16_f32 v115, v120, v121
	flat_store_dwordx4 v[128:129], v[112:115] offset:256
	v_pk_add_f32 v[108:109], v[108:109], v[144:145]
	v_pk_add_f32 v[110:111], v[110:111], v[142:143]
	v_lshlrev_b64 v[112:113], 11, v[150:151]
	v_pk_add_f32 v[104:105], v[104:105], v[140:141]
	v_pk_add_f32 v[106:107], v[106:107], v[138:139]
	v_lshl_add_u64 v[112:113], s[34:35], 0, v[112:113]
	v_pk_mul_f32 v[110:111], v[110:111], s[56:57] op_sel_hi:[1,0]
	v_pk_mul_f32 v[108:109], v[108:109], s[56:57] op_sel_hi:[1,0]
	v_pk_mul_f32 v[114:115], v[106:107], s[56:57] op_sel_hi:[1,0]
	v_pk_mul_f32 v[106:107], v[104:105], s[56:57] op_sel_hi:[1,0]
	v_lshl_add_u64 v[112:113], v[112:113], 0, v[176:177]
	v_cvt_pk_bf16_f32 v104, v108, v109
	v_cvt_pk_bf16_f32 v105, v110, v111
	v_cvt_pk_bf16_f32 v106, v106, v107
	v_cvt_pk_bf16_f32 v107, v114, v115
	v_pk_add_f32 v[96:97], v[96:97], v[132:133]
	v_pk_add_f32 v[98:99], v[98:99], v[130:131]
	v_pk_add_f32 v[88:89], v[88:89], v[136:137]
	v_pk_add_f32 v[90:91], v[90:91], v[134:135]
	flat_store_dwordx4 v[112:113], v[104:107]
	v_pk_mul_f32 v[98:99], v[98:99], s[56:57] op_sel_hi:[1,0]
	v_pk_mul_f32 v[96:97], v[96:97], s[56:57] op_sel_hi:[1,0]
	v_pk_mul_f32 v[104:105], v[90:91], s[56:57] op_sel_hi:[1,0]
	v_pk_mul_f32 v[90:91], v[88:89], s[56:57] op_sel_hi:[1,0]
	v_cvt_pk_bf16_f32 v88, v96, v97
	v_cvt_pk_bf16_f32 v89, v98, v99
	v_cvt_pk_bf16_f32 v90, v90, v91
	v_cvt_pk_bf16_f32 v91, v104, v105
	flat_store_dwordx4 v[112:113], v[88:91] offset:256
	v_pk_add_f32 v[92:93], v[92:93], v[140:141]
	v_pk_add_f32 v[94:95], v[94:95], v[138:139]
	v_lshlrev_b64 v[88:89], 11, v[148:149]
	v_lshl_add_u64 v[88:89], s[34:35], 0, v[88:89]
	v_lshl_add_u64 v[96:97], v[88:89], 0, v[176:177]
	v_pk_add_f32 v[88:89], v[100:101], v[144:145]
	v_pk_add_f32 v[90:91], v[102:103], v[142:143]
	v_pk_mul_f32 v[88:89], v[88:89], s[56:57] op_sel_hi:[1,0]
	v_pk_mul_f32 v[90:91], v[90:91], s[56:57] op_sel_hi:[1,0]
	v_pk_mul_f32 v[94:95], v[94:95], s[56:57] op_sel_hi:[1,0]
	v_pk_mul_f32 v[92:93], v[92:93], s[56:57] op_sel_hi:[1,0]
	v_cvt_pk_bf16_f32 v88, v88, v89
	v_cvt_pk_bf16_f32 v89, v90, v91
	v_cvt_pk_bf16_f32 v90, v92, v93
	v_cvt_pk_bf16_f32 v91, v94, v95
	v_pk_add_f32 v[80:81], v[80:81], v[132:133]
	v_pk_add_f32 v[82:83], v[82:83], v[130:131]
	v_pk_add_f32 v[72:73], v[72:73], v[136:137]
	v_pk_add_f32 v[74:75], v[74:75], v[134:135]
	flat_store_dwordx4 v[96:97], v[88:91]
	v_pk_mul_f32 v[82:83], v[82:83], s[56:57] op_sel_hi:[1,0]
	v_pk_mul_f32 v[80:81], v[80:81], s[56:57] op_sel_hi:[1,0]
	v_pk_mul_f32 v[88:89], v[74:75], s[56:57] op_sel_hi:[1,0]
	v_pk_mul_f32 v[74:75], v[72:73], s[56:57] op_sel_hi:[1,0]
	v_cvt_pk_bf16_f32 v72, v80, v81
	v_cvt_pk_bf16_f32 v73, v82, v83
	v_cvt_pk_bf16_f32 v74, v74, v75
	v_cvt_pk_bf16_f32 v75, v88, v89
	flat_store_dwordx4 v[96:97], v[72:75] offset:256
	v_pk_add_f32 v[76:77], v[76:77], v[140:141]
	v_pk_add_f32 v[78:79], v[78:79], v[138:139]
	v_lshlrev_b64 v[72:73], 11, v[146:147]
	v_lshl_add_u64 v[72:73], s[34:35], 0, v[72:73]
	v_lshl_add_u64 v[80:81], v[72:73], 0, v[176:177]
	v_pk_add_f32 v[72:73], v[84:85], v[144:145]
	v_pk_add_f32 v[74:75], v[86:87], v[142:143]
	v_pk_mul_f32 v[72:73], v[72:73], s[56:57] op_sel_hi:[1,0]
	v_pk_mul_f32 v[74:75], v[74:75], s[56:57] op_sel_hi:[1,0]
	v_pk_mul_f32 v[78:79], v[78:79], s[56:57] op_sel_hi:[1,0]
	v_pk_mul_f32 v[76:77], v[76:77], s[56:57] op_sel_hi:[1,0]
	v_cvt_pk_bf16_f32 v72, v72, v73
	v_cvt_pk_bf16_f32 v73, v74, v75
	v_cvt_pk_bf16_f32 v74, v76, v77
	v_cvt_pk_bf16_f32 v75, v78, v79
	v_pk_add_f32 v[68:69], v[68:69], v[132:133]
	v_pk_add_f32 v[70:71], v[70:71], v[130:131]
	v_pk_add_f32 v[64:65], v[64:65], v[136:137]
	v_pk_add_f32 v[66:67], v[66:67], v[134:135]
	flat_store_dwordx4 v[80:81], v[72:75]
	v_pk_mul_f32 v[70:71], v[70:71], s[56:57] op_sel_hi:[1,0]
	v_pk_mul_f32 v[68:69], v[68:69], s[56:57] op_sel_hi:[1,0]
	v_pk_mul_f32 v[72:73], v[66:67], s[56:57] op_sel_hi:[1,0]
	v_pk_mul_f32 v[66:67], v[64:65], s[56:57] op_sel_hi:[1,0]
	v_cvt_pk_bf16_f32 v64, v68, v69
	v_cvt_pk_bf16_f32 v65, v70, v71
	v_cvt_pk_bf16_f32 v66, v66, v67
	v_cvt_pk_bf16_f32 v67, v72, v73
	v_pk_add_f32 v[60:61], v[60:61], v[144:145]
	flat_store_dwordx4 v[80:81], v[64:67] offset:256
	v_pk_add_f32 v[62:63], v[62:63], v[142:143]
	v_pk_mul_f32 v[60:61], v[60:61], s[56:57] op_sel_hi:[1,0]
	v_lshl_add_u64 v[64:65], v[128:129], 0, s[0:1]
	v_pk_add_f32 v[56:57], v[56:57], v[140:141]
	v_pk_add_f32 v[58:59], v[58:59], v[138:139]
	s_mov_b32 s0, 0x40000
	v_pk_mul_f32 v[62:63], v[62:63], s[56:57] op_sel_hi:[1,0]
	v_pk_mul_f32 v[66:67], v[58:59], s[56:57] op_sel_hi:[1,0]
	v_pk_mul_f32 v[58:59], v[56:57], s[56:57] op_sel_hi:[1,0]
	v_cvt_pk_bf16_f32 v56, v60, v61
	v_add_co_u32_e32 v60, vcc, s0, v128
	v_cvt_pk_bf16_f32 v57, v62, v63
	v_cvt_pk_bf16_f32 v58, v58, v59
	v_cvt_pk_bf16_f32 v59, v66, v67
	v_addc_co_u32_e32 v61, vcc, 0, v129, vcc
	v_pk_add_f32 v[48:49], v[48:49], v[132:133]
	v_pk_add_f32 v[50:51], v[50:51], v[130:131]
	v_pk_add_f32 v[40:41], v[40:41], v[136:137]
	v_pk_add_f32 v[42:43], v[42:43], v[134:135]
	flat_store_dwordx4 v[60:61], v[56:59]
	v_pk_mul_f32 v[50:51], v[50:51], s[56:57] op_sel_hi:[1,0]
	v_pk_mul_f32 v[48:49], v[48:49], s[56:57] op_sel_hi:[1,0]
	v_pk_mul_f32 v[56:57], v[42:43], s[56:57] op_sel_hi:[1,0]
	v_pk_mul_f32 v[42:43], v[40:41], s[56:57] op_sel_hi:[1,0]
	v_cvt_pk_bf16_f32 v40, v48, v49
	v_cvt_pk_bf16_f32 v41, v50, v51
	v_cvt_pk_bf16_f32 v42, v42, v43
	v_cvt_pk_bf16_f32 v43, v56, v57
	flat_store_dwordx4 v[64:65], v[40:43] offset:256
	s_mov_b64 s[0:1], 0x48000
	v_pk_add_f32 v[44:45], v[44:45], v[140:141]
	v_pk_add_f32 v[40:41], v[52:53], v[144:145]
	v_pk_add_f32 v[42:43], v[54:55], v[142:143]
	v_lshl_add_u64 v[48:49], v[128:129], 0, s[0:1]
	v_pk_mul_f32 v[42:43], v[42:43], s[56:57] op_sel_hi:[1,0]
	v_pk_mul_f32 v[40:41], v[40:41], s[56:57] op_sel_hi:[1,0]
	v_pk_add_f32 v[46:47], v[46:47], v[138:139]
	v_pk_mul_f32 v[44:45], v[44:45], s[56:57] op_sel_hi:[1,0]
	s_mov_b32 s0, 0x48000
	v_pk_mul_f32 v[46:47], v[46:47], s[56:57] op_sel_hi:[1,0]
	v_cvt_pk_bf16_f32 v40, v40, v41
	v_cvt_pk_bf16_f32 v41, v42, v43
	v_cvt_pk_bf16_f32 v42, v44, v45
	v_add_co_u32_e32 v44, vcc, s0, v128
	v_cvt_pk_bf16_f32 v43, v46, v47
	s_nop 0
	v_addc_co_u32_e32 v45, vcc, 0, v129, vcc
	v_pk_add_f32 v[32:33], v[32:33], v[132:133]
	v_pk_add_f32 v[34:35], v[34:35], v[130:131]
	v_pk_add_f32 v[24:25], v[24:25], v[136:137]
	v_pk_add_f32 v[26:27], v[26:27], v[134:135]
	flat_store_dwordx4 v[44:45], v[40:43]
	v_pk_mul_f32 v[34:35], v[34:35], s[56:57] op_sel_hi:[1,0]
	v_pk_mul_f32 v[32:33], v[32:33], s[56:57] op_sel_hi:[1,0]
	v_pk_mul_f32 v[40:41], v[26:27], s[56:57] op_sel_hi:[1,0]
	v_pk_mul_f32 v[26:27], v[24:25], s[56:57] op_sel_hi:[1,0]
	v_cvt_pk_bf16_f32 v24, v32, v33
	v_cvt_pk_bf16_f32 v25, v34, v35
	v_cvt_pk_bf16_f32 v26, v26, v27
	v_cvt_pk_bf16_f32 v27, v40, v41
	flat_store_dwordx4 v[48:49], v[24:27] offset:256
	s_mov_b64 s[0:1], 0x50000
	v_pk_add_f32 v[28:29], v[28:29], v[140:141]
	v_pk_add_f32 v[24:25], v[36:37], v[144:145]
	v_pk_add_f32 v[26:27], v[38:39], v[142:143]
	v_lshl_add_u64 v[32:33], v[128:129], 0, s[0:1]
	v_pk_mul_f32 v[26:27], v[26:27], s[56:57] op_sel_hi:[1,0]
	v_pk_mul_f32 v[24:25], v[24:25], s[56:57] op_sel_hi:[1,0]
	v_pk_add_f32 v[30:31], v[30:31], v[138:139]
	v_pk_mul_f32 v[28:29], v[28:29], s[56:57] op_sel_hi:[1,0]
	s_mov_b32 s0, 0x50000
	v_pk_mul_f32 v[30:31], v[30:31], s[56:57] op_sel_hi:[1,0]
	v_cvt_pk_bf16_f32 v24, v24, v25
	v_cvt_pk_bf16_f32 v25, v26, v27
	v_cvt_pk_bf16_f32 v26, v28, v29
	v_add_co_u32_e32 v28, vcc, s0, v128
	v_cvt_pk_bf16_f32 v27, v30, v31
	s_nop 0
	v_addc_co_u32_e32 v29, vcc, 0, v129, vcc
	v_pk_add_f32 v[16:17], v[16:17], v[132:133]
	v_pk_add_f32 v[18:19], v[18:19], v[130:131]
	v_pk_add_f32 v[8:9], v[8:9], v[136:137]
	v_pk_add_f32 v[10:11], v[10:11], v[134:135]
	flat_store_dwordx4 v[28:29], v[24:27]
	v_pk_mul_f32 v[18:19], v[18:19], s[56:57] op_sel_hi:[1,0]
	v_pk_mul_f32 v[16:17], v[16:17], s[56:57] op_sel_hi:[1,0]
	v_pk_mul_f32 v[24:25], v[10:11], s[56:57] op_sel_hi:[1,0]
	v_pk_mul_f32 v[10:11], v[8:9], s[56:57] op_sel_hi:[1,0]
	v_cvt_pk_bf16_f32 v8, v16, v17
	v_cvt_pk_bf16_f32 v9, v18, v19
	v_cvt_pk_bf16_f32 v10, v10, v11
	v_cvt_pk_bf16_f32 v11, v24, v25
	flat_store_dwordx4 v[32:33], v[8:11] offset:256
	s_mov_b64 s[0:1], 0x58000
	v_pk_add_f32 v[12:13], v[12:13], v[140:141]
	v_pk_add_f32 v[8:9], v[20:21], v[144:145]
	v_pk_add_f32 v[10:11], v[22:23], v[142:143]
	v_lshl_add_u64 v[16:17], v[128:129], 0, s[0:1]
	v_pk_mul_f32 v[10:11], v[10:11], s[56:57] op_sel_hi:[1,0]
	v_pk_mul_f32 v[8:9], v[8:9], s[56:57] op_sel_hi:[1,0]
	v_pk_add_f32 v[14:15], v[14:15], v[138:139]
	v_pk_mul_f32 v[12:13], v[12:13], s[56:57] op_sel_hi:[1,0]
	s_mov_b32 s0, 0x58000
	v_pk_mul_f32 v[14:15], v[14:15], s[56:57] op_sel_hi:[1,0]
	v_cvt_pk_bf16_f32 v8, v8, v9
	v_cvt_pk_bf16_f32 v9, v10, v11
	v_cvt_pk_bf16_f32 v10, v12, v13
	v_add_co_u32_e32 v12, vcc, s0, v128
	v_cvt_pk_bf16_f32 v11, v14, v15
	s_nop 0
	v_addc_co_u32_e32 v13, vcc, 0, v129, vcc
	v_pk_add_f32 v[4:5], v[4:5], v[132:133]
	v_pk_add_f32 v[6:7], v[6:7], v[130:131]
	v_pk_add_f32 v[0:1], v[0:1], v[136:137]
	v_pk_add_f32 v[2:3], v[2:3], v[134:135]
	flat_store_dwordx4 v[12:13], v[8:11]
	v_pk_mul_f32 v[6:7], v[6:7], s[56:57] op_sel_hi:[1,0]
	v_pk_mul_f32 v[4:5], v[4:5], s[56:57] op_sel_hi:[1,0]
	v_pk_mul_f32 v[8:9], v[2:3], s[56:57] op_sel_hi:[1,0]
	v_pk_mul_f32 v[2:3], v[0:1], s[56:57] op_sel_hi:[1,0]
	v_cvt_pk_bf16_f32 v0, v4, v5
	v_cvt_pk_bf16_f32 v1, v6, v7
	v_cvt_pk_bf16_f32 v2, v2, v3
	v_cvt_pk_bf16_f32 v3, v8, v9
	flat_store_dwordx4 v[16:17], v[0:3] offset:256
	s_waitcnt vmcnt(0)
	s_barrier

.LBB0_612:
	s_andn2_b64 vcc, exec, s[0:1]
	s_cbranch_vccnz .LBB0_558
	s_mov_b64 s[58:59], s[94:95]
	s_mov_b64 s[42:43], s[94:95]
	s_mov_b64 s[46:47], s[94:95]
	s_mov_b64 s[34:35], s[94:95]
	s_mov_b64 s[0:1], s[94:95]
	s_add_u32 s0, s0, s76
	s_addc_u32 s1, s1, 0
	s_add_u32 s0, s0, 0x20000
	s_addc_u32 s1, s1, 0
	s_ashr_i32 s22, s77, 7
	s_add_i32 s36, s22, 8
	s_lshl_b32 s40, s36, 11
	s_lshl_b32 s36, s36, 12
	s_bfe_u32 s3, s77, 0x20005
	s_add_i32 s41, s36, 0xffffc000
	s_cmp_lt_i32 s22, 0
	s_cselect_b64 s[68:69], -1, 0
	s_and_b64 s[36:37], s[68:69], exec
	s_cselect_b32 s40, s40, s41
	s_lshl_b32 s22, s77, 7
	s_and_b32 s78, s22, 0xf80
	s_add_i32 s36, s40, s78
	s_ashr_i32 s37, s36, 31
	s_lshl_b64 s[60:61], s[36:37], 10
	s_add_u32 s22, s58, s60
	v_mov_b32_e32 v18, v226
	s_addc_u32 s37, s59, s61
	s_lshl_b32 s41, s3, 8
	s_add_u32 s58, s22, s41
	v_lshlrev_b32_e32 v0, 4, v18
	v_add_u32_e32 v30, 0x200, v18
	v_add_u32_e32 v10, 0x400, v18
	v_add_u32_e32 v12, 0x600, v18
	s_addc_u32 s59, s37, 0
	v_and_b32_e32 v20, 0xf0, v0
	v_mov_b32_e32 v21, v177
	v_ashrrev_i32_e32 v22, 4, v18
	v_ashrrev_i32_e32 v24, 4, v30
	v_ashrrev_i32_e32 v26, 4, v10
	v_ashrrev_i32_e32 v28, 4, v12
	s_mul_i32 s22, s3, 0x208
	v_lshl_add_u64 v[0:1], s[58:59], 0, v[20:21]
	s_mov_b64 s[14:15], 0x8b00000
	v_ashrrev_i32_e32 v23, 31, v22
	v_ashrrev_i32_e32 v25, 31, v24
	v_ashrrev_i32_e32 v27, 31, v26
	v_ashrrev_i32_e32 v29, 31, v28
	v_add_u32_e32 v32, s22, v18
	v_lshl_add_u64 v[8:9], v[0:1], 0, s[14:15]
	v_lshlrev_b64 v[16:17], 10, v[22:23]
	v_lshlrev_b64 v[2:3], 10, v[24:25]
	v_lshlrev_b64 v[10:11], 10, v[26:27]
	v_lshlrev_b64 v[12:13], 10, v[28:29]
	v_ashrrev_i32_e32 v33, 31, v32
	v_lshl_add_u64 v[0:1], v[8:9], 0, v[16:17]
	v_lshl_add_u64 v[2:3], v[8:9], 0, v[2:3]
	v_lshl_add_u64 v[10:11], v[8:9], 0, v[10:11]
	v_lshl_add_u64 v[8:9], v[8:9], 0, v[12:13]
	v_lshl_add_u64 v[32:33], v[32:33], 2, s[0:1]
	global_load_dwordx4 v[4:7], v[0:1], off
	s_nop 0
	global_load_dwordx4 v[0:3], v[2:3], off
	s_nop 0
	global_load_dwordx4 v[12:15], v[10:11], off
	s_nop 0
	global_load_dwordx4 v[8:11], v[8:9], off
	v_readfirstlane_b32 s58, v18
	flat_load_dword v21, v[32:33]
	v_cmp_gt_i32_e32 vcc, 8, v18
	v_mov_b32_e32 v19, 0
	v_mov_b32_e32 v25, 0
	s_and_saveexec_b64 s[70:71], vcc
	s_cbranch_execz .LBB0_615
	v_add_u32_e32 v30, s22, v30
	v_ashrrev_i32_e32 v31, 31, v30
	v_lshl_add_u64 v[30:31], v[30:31], 2, s[0:1]
	flat_load_dword v25, v[30:31]

.LBB0_617:
	s_or_b64 exec, exec, s[70:71]
	s_ashr_i32 s41, s40, 31
	s_lshl_b64 s[70:71], s[40:41], 10
	s_add_u32 s37, s42, s70
	s_addc_u32 s48, s43, s71
	s_lshl_b32 s3, s22, 1
	s_add_u32 s37, s37, s3
	s_addc_u32 s48, s48, 0
	s_add_u32 s60, s37, 0xab00000
	s_addc_u32 s61, s48, 0
	v_and_b32_e32 v27, 15, v18
	v_lshlrev_b64 v[32:33], 10, v[22:23]
	s_lshl_b32 s52, s22, 16
	v_lshlrev_b32_e32 v176, 4, v27
	v_lshl_add_u64 v[32:33], s[60:61], 0, v[32:33]
	s_add_u32 s37, s46, s52
	v_lshl_add_u64 v[36:37], v[32:33], 0, v[176:177]
	s_mov_b32 s7, 0x8000
	s_addc_u32 s48, s47, 0
	s_lshl_b64 s[72:73], s[40:41], 1
	v_ashrrev_i32_e32 v34, 3, v18
	v_lshl_add_u64 v[30:31], s[60:61], 0, v[16:17]
	v_add_co_u32_e64 v32, s[40:41], s7, v36
	s_add_u32 s62, s37, s72
	v_lshl_add_u64 v[30:31], v[30:31], 0, v[176:177]
	v_addc_co_u32_e64 v33, s[40:41], 0, v37, s[40:41]
	v_ashrrev_i32_e32 v35, 31, v34
	s_addc_u32 s63, s48, s73
	v_and_b32_e32 v29, 7, v18
	s_waitcnt vmcnt(0)
	global_load_dwordx4 v[96:99], v[30:31], off
	global_load_dwordx4 v[100:103], v[32:33], off
	v_lshlrev_b64 v[32:33], 16, v[34:35]
	v_lshl_add_u64 v[38:39], s[62:63], 0, v[32:33]
	v_lshlrev_b32_e32 v30, 4, v29
	v_mov_b32_e32 v31, v177
	v_lshl_add_u64 v[38:39], v[38:39], 0, v[30:31]
	s_mov_b32 s7, 0xcb00000
	s_mov_b64 s[14:15], 0xcb00000
	v_add_co_u32_e64 v42, s[40:41], s7, v38
	v_lshl_add_u64 v[40:41], v[38:39], 0, s[14:15]
	s_nop 0
	v_addc_co_u32_e64 v43, s[40:41], 0, v39, s[40:41]
	s_mov_b64 s[14:15], 0xcf00000
	s_mov_b32 s7, 0xcf00000
	v_lshl_add_u64 v[44:45], v[38:39], 0, s[14:15]
	v_add_co_u32_e64 v38, s[40:41], s7, v38
	v_readlane_b32 s7, v255, 23
	s_nop 0
	v_addc_co_u32_e64 v39, s[40:41], 0, v39, s[40:41]
	v_add_co_u32_e64 v46, s[40:41], s9, v36
	s_nop 1
	v_addc_co_u32_e64 v47, s[40:41], 0, v37, s[40:41]
	v_add_co_u32_e64 v36, s[40:41], s10, v36
	s_nop 1
	v_addc_co_u32_e64 v37, s[40:41], 0, v37, s[40:41]
	global_load_dwordx4 v[104:107], v[46:47], off
	global_load_dwordx4 v[108:111], v[36:37], off
	global_load_dwordx4 v[120:123], v[42:43], off
	global_load_dwordx4 v[112:115], v[40:41], off offset:128
	global_load_dwordx4 v[124:127], v[38:39], off
	global_load_dwordx4 v[116:119], v[44:45], off offset:128
	v_add_u32_e32 v36, s7, v20
	v_mul_lo_u32 v20, v22, s12
	v_add_u32_e32 v22, v36, v20
	s_waitcnt lgkmcnt(0)
	ds_write_b128 v22, v[4:7]
	v_mad_u64_u32 v[4:5], s[40:41], v24, s12, v[36:37]
	ds_write_b128 v4, v[0:3]
	v_mad_u64_u32 v[0:1], s[40:41], v26, s12, v[36:37]
	ds_write_b128 v0, v[12:15]
	v_mad_u64_u32 v[0:1], s[40:41], v28, s12, v[36:37]
	ds_write_b128 v0, v[8:11]
	v_lshl_add_u32 v0, v18, 2, 0
	v_add_u32_e32 v1, 0x11800, v0
	ds_write_b32 v1, v21
	s_and_saveexec_b64 s[40:41], vcc
	ds_write_b32 v1, v25 offset:2048
	s_or_b64 exec, exec, s[40:41]
	s_and_saveexec_b64 s[40:41], s[0:1]
	v_add_u32_e32 v0, 0x1a900, v0
	ds_write_b32 v0, v19
	s_or_b64 exec, exec, s[40:41]
	s_ashr_i32 s60, s58, 8
	s_lshl_b32 s40, s60, 7
	s_bfe_u32 s61, s58, 0x20006
	s_add_i32 s0, s40, 0
	s_lshr_b32 s59, s58, 6
	v_and_b32_e32 v2, 31, v18
	s_lshl_b32 s37, s61, 5
	s_add_i32 s0, s0, 0x12100
	v_or_b32_e32 v1, s37, v2
	v_mov_b32_e32 v3, s0
	s_and_b64 s[0:1], s[68:69], exec
	v_lshlrev_b32_e32 v0, 3, v18
	v_mad_u32_u24 v3, v1, s12, v3
	v_add_u32_e32 v1, 0, v20
	s_movk_i32 s0, 0x90
	v_and_b32_e32 v0, 8, v0
	v_add_u32_e32 v239, v1, v176
	v_mul_lo_u32 v1, v34, s0
	v_and_or_b32 v0, v30, s8, v0
	v_add_u32_e32 v1, 0, v1
	s_mul_i32 s0, s60, 0x410
	v_bfe_u32 v236, v18, 5, 1
	s_cselect_b32 s62, 32, 64
	v_add_u32_e32 v240, v1, v0
	s_add_i32 s63, s0, 0
	s_or_b32 s69, s37, s78
	v_mad_u32_u24 v0, v2, s12, 0
	v_lshlrev_b32_e32 v1, 7, v2
	v_lshlrev_b32_e32 v237, 4, v236
	s_add_i32 s63, s63, 0x11800
	v_add_u32_e32 v4, s40, v0
	v_sub_u32_e32 v0, v0, v1
	s_add_i32 s68, s69, 0x9f
	s_addk_i32 s69, 0x5f
	v_add_u32_e32 v243, v0, v237
	v_lshl_add_u64 v[0:1], s[52:53], 0, v[32:33]
	v_mov_b32_e32 v31, v177
	s_add_u32 s0, s46, s72
	v_lshl_add_u64 v[0:1], v[0:1], 0, v[30:31]
	s_addc_u32 s1, s47, s73
	v_lshl_add_u64 v[0:1], s[0:1], 0, v[0:1]
	s_mov_b64 s[0:1], 0xcf00180
	v_lshl_add_u64 v[190:191], v[0:1], 0, s[0:1]
	s_lshl_b32 s0, s77, 3
	s_and_b32 s0, s0, 0x300
	s_add_u32 s0, s0, s70
	s_addc_u32 s1, 0, s71
	v_lshl_add_u64 v[0:1], s[0:1], 0, v[16:17]
	v_lshl_add_u64 v[0:1], v[0:1], 0, v[176:177]
	v_lshlrev_b32_e32 v235, 2, v236
	v_lshl_add_u64 v[0:1], s[42:43], 0, v[0:1]
	s_mov_b64 s[0:1], 0xab38000
	v_lshl_add_u64 v[192:193], v[0:1], 0, s[0:1]
	v_sub_u32_e32 v0, v235, v2
	v_subrev_u32_e32 v0, s37, v0
	s_add_i32 s0, s37, s78
	v_mov_b32_e32 v248, 0
	v_lshlrev_b32_e32 v233, 3, v27
	v_and_b32_e32 v234, 63, v18
	v_add_u32_e32 v241, 0x8800, v240
	v_add_u32_e32 v242, 0xa800, v240
	v_mul_u32_u24_e32 v238, 0x110, v2
	v_add_u32_e32 v244, 0xd000, v243
	s_mov_b32 s22, 3
	v_subrev_u32_e32 v245, s78, v0
	s_mov_b32 s42, 0
	s_sub_i32 s43, 0, s0
	v_add_u32_e32 v246, v4, v237
	v_add_u32_e32 v247, v3, v237
	v_mov_b32_e32 v0, 0
	v_mov_b32_e32 v1, v248
	v_mov_b32_e32 v2, v248
	v_mov_b32_e32 v3, v248
	v_mov_b32_e32 v4, v248
	v_mov_b32_e32 v5, v248
	v_mov_b32_e32 v6, v248
	v_mov_b32_e32 v7, v248
	v_mov_b32_e32 v8, v248
	v_mov_b32_e32 v9, v248
	v_mov_b32_e32 v10, v248
	v_mov_b32_e32 v11, v248
	v_mov_b32_e32 v12, v248
	v_mov_b32_e32 v13, v248
	v_mov_b32_e32 v14, v248
	v_mov_b32_e32 v15, v248
	v_mov_b32_e32 v16, 0
	v_mov_b32_e32 v17, v248
	v_mov_b32_e32 v18, v248
	v_mov_b32_e32 v19, v248
	v_mov_b32_e32 v20, v248
	v_mov_b32_e32 v21, v248
	v_mov_b32_e32 v22, v248
	v_mov_b32_e32 v23, v248
	v_mov_b32_e32 v24, v248
	v_mov_b32_e32 v25, v248
	v_mov_b32_e32 v26, v248
	v_mov_b32_e32 v27, v248
	v_mov_b32_e32 v28, v248
	v_mov_b32_e32 v29, v248
	v_mov_b32_e32 v30, v248
	v_mov_b32_e32 v31, v248
	v_mov_b32_e32 v32, 0
	v_mov_b32_e32 v33, v248
	v_mov_b32_e32 v34, v248
	v_mov_b32_e32 v35, v248
	v_mov_b32_e32 v36, v248
	v_mov_b32_e32 v37, v248
	v_mov_b32_e32 v38, v248
	v_mov_b32_e32 v39, v248
	v_mov_b32_e32 v40, v248
	v_mov_b32_e32 v41, v248
	v_mov_b32_e32 v42, v248
	v_mov_b32_e32 v43, v248
	v_mov_b32_e32 v44, v248
	v_mov_b32_e32 v45, v248
	v_mov_b32_e32 v46, v248
	v_mov_b32_e32 v47, v248
	v_mov_b32_e32 v48, 0
	v_mov_b32_e32 v49, v248
	v_mov_b32_e32 v50, v248
	v_mov_b32_e32 v51, v248
	v_mov_b32_e32 v52, v248
	v_mov_b32_e32 v53, v248
	v_mov_b32_e32 v54, v248
	v_mov_b32_e32 v55, v248
	v_mov_b32_e32 v56, v248
	v_mov_b32_e32 v57, v248
	v_mov_b32_e32 v58, v248
	v_mov_b32_e32 v59, v248
	v_mov_b32_e32 v60, v248
	v_mov_b32_e32 v61, v248
	v_mov_b32_e32 v62, v248
	v_mov_b32_e32 v63, v248
	s_waitcnt vmcnt(0)
	ds_write_b128 v239, v[96:99]
	ds_write_b128 v239, v[100:103] offset:8704
	ds_write2_b64 v241, v[120:121], v[122:123] offset1:2
	ds_write2_b64 v242, v[124:125], v[126:127] offset0:128 offset1:130
	s_waitcnt lgkmcnt(0)
	s_barrier
	s_branch .LBB0_623
.LBB0_622:
	s_waitcnt lgkmcnt(0)
	s_barrier
	s_add_i32 s22, s22, 2
	s_addk_i32 s42, 0x80
	v_lshl_add_u64 v[190:191], v[190:191], 0, s[26:27]
	s_cmp_ge_u32 s46, s62
	v_lshl_add_u64 v[192:193], v[192:193], 0, s[84:85]
	s_cbranch_scc1 .LBB0_637

.LBB0_625:
	s_add_i32 s47, s43, s42
	s_setprio 1
	ds_read_b128 v[140:143], v247
	ds_read_b128 v[136:139], v247 offset:32
	ds_read_b128 v[132:135], v247 offset:64
	ds_read_b128 v[128:131], v247 offset:96
	ds_read_b128 v[172:175], v246
	ds_read_b128 v[168:171], v246 offset:32
	ds_read_b128 v[164:167], v246 offset:64
	ds_read_b128 v[160:163], v246 offset:96
	ds_read_b128 v[156:159], v246 offset:8704
	ds_read_b128 v[152:155], v246 offset:8736
	ds_read_b128 v[148:151], v246 offset:8768
	ds_read_b128 v[144:147], v246 offset:8800
	s_cmp_lt_u32 s42, s68
	s_cselect_b64 s[40:41], -1, 0
	s_cmpk_gt_i32 s47, 0xff41
	s_cselect_b64 s[70:71], -1, 0
	s_and_b64 s[70:71], s[40:41], s[70:71]
	s_and_b64 vcc, exec, s[70:71]
	s_cbranch_vccnz .LBB0_627
	s_and_b64 s[40:41], s[40:41], exec
	s_cselect_b32 s40, 0, 0x400
	s_add_i32 s40, s63, s40
	v_mov_b32_e32 v64, s40
	ds_read_b32 v225, v64
	v_add_u32_e32 v249, s42, v245
	s_cmp_eq_u64 s[0:1], 0
	s_waitcnt lgkmcnt(8)
	v_mfma_f32_32x32x16_bf16 v[64:79], v[172:175], v[140:143], 0
	s_cbranch_scc1 .La2t0_nl0
	v_add_co_u32_e32 v186, vcc, 0xfffe8000, v192
	s_nop 1
	v_addc_co_u32_e32 v187, vcc, -1, v193, vcc
	global_load_dwordx4 v[96:99], v[186:187], off
.La2t0_nl0:
	s_waitcnt lgkmcnt(7)
	v_mfma_f32_32x32x16_bf16 v[64:79], v[168:171], v[136:139], v[64:79]
	s_cbranch_scc1 .La2t0_nl1
	v_add_co_u32_e32 v186, vcc, 0xffff0000, v192
	s_nop 1
	v_addc_co_u32_e32 v187, vcc, -1, v193, vcc
	global_load_dwordx4 v[100:103], v[186:187], off
.La2t0_nl1:
	s_waitcnt lgkmcnt(6)
	v_mfma_f32_32x32x16_bf16 v[64:79], v[164:167], v[132:135], v[64:79]
	s_cbranch_scc1 .La2t0_nl2
	v_add_co_u32_e32 v186, vcc, 0xffbfff80, v190
	s_nop 1
	v_addc_co_u32_e32 v187, vcc, -1, v191, vcc
	global_load_dwordx4 v[120:123], v[186:187], off
.La2t0_nl2:
	s_waitcnt lgkmcnt(5)
	v_mfma_f32_32x32x16_bf16 v[64:79], v[160:163], v[128:131], v[64:79]
	s_cbranch_scc1 .La2t0_nl3
	v_add_co_u32_e32 v186, vcc, 0xffffff80, v190
	s_nop 1
	v_addc_co_u32_e32 v187, vcc, -1, v191, vcc
	global_load_dwordx4 v[124:127], v[186:187], off
.La2t0_nl3:
	s_waitcnt lgkmcnt(4)
	v_mfma_f32_32x32x16_bf16 v[80:95], v[156:159], v[140:143], 0
	s_waitcnt lgkmcnt(0)
	s_nop 10
	v_add_f32_e32 v64, v64, v225
	v_add_f32_e32 v65, v65, v225
	v_add_f32_e32 v66, v66, v225
	v_add_f32_e32 v67, v67, v225
	v_add_f32_e32 v68, v68, v225
	v_add_f32_e32 v69, v69, v225
	v_add_f32_e32 v70, v70, v225
	v_add_f32_e32 v71, v71, v225
	v_add_f32_e32 v72, v72, v225
	v_add_f32_e32 v73, v73, v225
	v_mfma_f32_32x32x16_bf16 v[80:95], v[152:155], v[136:139], v[80:95]
	v_add_f32_e32 v74, v74, v225
	v_add_f32_e32 v75, v75, v225
	v_add_f32_e32 v76, v76, v225
	v_add_f32_e32 v77, v77, v225
	v_add_f32_e32 v78, v78, v225
	v_add_f32_e32 v79, v79, v225
	v_exp_f32_e32 v194, v64
	v_exp_f32_e32 v195, v65
	v_exp_f32_e32 v196, v66
	v_exp_f32_e32 v197, v67
	v_mfma_f32_32x32x16_bf16 v[80:95], v[148:151], v[132:135], v[80:95]
	v_exp_f32_e32 v198, v68
	v_exp_f32_e32 v199, v69
	v_exp_f32_e32 v200, v70
	v_exp_f32_e32 v201, v71
	v_exp_f32_e32 v202, v72
	v_exp_f32_e32 v203, v73
	v_exp_f32_e32 v204, v74
	v_exp_f32_e32 v205, v75
	v_exp_f32_e32 v206, v76
	v_exp_f32_e32 v207, v77
	v_mfma_f32_32x32x16_bf16 v[80:95], v[144:147], v[128:131], v[80:95]
	ds_read_b128 v[144:147], v243 offset:34816
	ds_read_b128 v[148:151], v243 offset:34848
	ds_read_b128 v[152:155], v243 offset:39424
	ds_read_b128 v[156:159], v243 offset:39456
	ds_read_b128 v[128:131], v243 offset:44032
	ds_read_b128 v[132:135], v243 offset:44064
	ds_read_b128 v[136:139], v243 offset:48640
	ds_read_b128 v[140:143], v243 offset:48672
	v_exp_f32_e32 v208, v78
	v_exp_f32_e32 v209, v79
	v_cvt_pk_bf16_f32 v64, v194, v195
	v_cvt_pk_bf16_f32 v65, v196, v197
	v_cvt_pk_bf16_f32 v66, v198, v199
	v_cvt_pk_bf16_f32 v67, v200, v201
	v_cvt_pk_bf16_f32 v68, v202, v203
	v_cvt_pk_bf16_f32 v69, v204, v205
	v_cvt_pk_bf16_f32 v70, v206, v207
	v_cvt_pk_bf16_f32 v71, v208, v209
	v_add_f32_e32 v80, v80, v225
	v_add_f32_e32 v81, v81, v225
	v_add_f32_e32 v82, v82, v225
	v_add_f32_e32 v83, v83, v225
	v_add_f32_e32 v84, v84, v225
	v_add_f32_e32 v85, v85, v225
	v_add_f32_e32 v86, v86, v225
	v_add_f32_e32 v87, v87, v225
	v_add_f32_e32 v88, v88, v225
	v_add_f32_e32 v89, v89, v225
	s_waitcnt lgkmcnt(7)
	v_mfma_f32_32x32x16_bf16 v[48:63], v[144:147], v[64:67], v[48:63]
	s_cmp_eq_u64 s[0:1], 0
	s_cbranch_scc1 .La2t0_lv_a
	s_waitcnt vmcnt(4)
	s_branch .La2t0_lv_b

.LBB0_627:
	s_cmp_eq_u64 s[0:1], 0
	s_cbranch_scc1 .La2t0_nrl
	v_add_co_u32_e32 v64, vcc, 0xfffe8000, v192
	s_nop 1
	v_addc_co_u32_e32 v65, vcc, -1, v193, vcc
	v_add_co_u32_e32 v66, vcc, 0xffff0000, v192
	s_nop 1
	v_addc_co_u32_e32 v67, vcc, -1, v193, vcc
	global_load_dwordx4 v[96:99], v[64:65], off
	global_load_dwordx4 v[100:103], v[66:67], off
	v_add_co_u32_e32 v64, vcc, 0xffbfff80, v190
	s_nop 1
	v_addc_co_u32_e32 v65, vcc, -1, v191, vcc
	v_add_co_u32_e32 v66, vcc, 0xffffff80, v190
	s_nop 1
	v_addc_co_u32_e32 v67, vcc, -1, v191, vcc
	global_load_dwordx4 v[120:123], v[64:65], off
	global_load_dwordx4 v[124:127], v[66:67], off

.LBB0_629:
	s_setprio 0
	s_waitcnt lgkmcnt(0)
	ds_read_b128 v[128:131], v243 offset:34816
	ds_read_b128 v[132:135], v243 offset:34848
	ds_read_b128 v[136:139], v243 offset:34880
	ds_read_b128 v[140:143], v243 offset:34912
	s_nop 1
	v_add_f32_e32 v64, v64, v225
	v_exp_f32_e32 v194, v64
	v_add_f32_e32 v64, v65, v225
	v_exp_f32_e32 v195, v64
	v_add_f32_e32 v64, v66, v225
	v_exp_f32_e32 v196, v64
	v_add_f32_e32 v64, v67, v225
	v_exp_f32_e32 v197, v64
	v_add_f32_e32 v64, v68, v225
	v_exp_f32_e32 v198, v64
	v_add_f32_e32 v64, v69, v225
	v_exp_f32_e32 v199, v64
	v_add_f32_e32 v64, v70, v225
	v_exp_f32_e32 v200, v64
	v_add_f32_e32 v64, v71, v225
	v_exp_f32_e32 v201, v64
	v_add_f32_e32 v64, v72, v225
	v_exp_f32_e32 v202, v64
	v_add_f32_e32 v64, v73, v225
	v_exp_f32_e32 v203, v64
	v_add_f32_e32 v64, v74, v225
	v_exp_f32_e32 v204, v64
	v_add_f32_e32 v64, v75, v225
	v_exp_f32_e32 v205, v64
	v_add_f32_e32 v64, v76, v225
	v_exp_f32_e32 v206, v64
	v_add_f32_e32 v64, v77, v225
	v_exp_f32_e32 v207, v64
	v_add_f32_e32 v64, v78, v225
	v_exp_f32_e32 v208, v64
	v_add_f32_e32 v64, v79, v225
	v_exp_f32_e32 v209, v64
	v_add_f32_e32 v64, v225, v80
	v_exp_f32_e32 v210, v64
	v_add_f32_e32 v64, v225, v81
	v_exp_f32_e32 v211, v64
	v_add_f32_e32 v64, v225, v82
	v_exp_f32_e32 v212, v64
	v_add_f32_e32 v64, v225, v83
	v_exp_f32_e32 v213, v64
	v_add_f32_e32 v64, v225, v84
	v_exp_f32_e32 v214, v64
	v_add_f32_e32 v64, v225, v85
	v_exp_f32_e32 v215, v64
	v_add_f32_e32 v64, v225, v86
	v_exp_f32_e32 v216, v64
	v_add_f32_e32 v64, v225, v87
	v_exp_f32_e32 v217, v64
	v_add_f32_e32 v64, v225, v88
	v_exp_f32_e32 v218, v64
	v_add_f32_e32 v64, v225, v89
	v_exp_f32_e32 v219, v64
	v_add_f32_e32 v64, v225, v90
	v_exp_f32_e32 v220, v64
	v_add_f32_e32 v64, v225, v91
	v_exp_f32_e32 v221, v64
	v_add_f32_e32 v64, v225, v92
	v_exp_f32_e32 v222, v64
	v_add_f32_e32 v64, v225, v93
	v_exp_f32_e32 v223, v64
	v_add_f32_e32 v64, v225, v94
	v_exp_f32_e32 v224, v64
	v_add_f32_e32 v64, v225, v95
	v_exp_f32_e32 v225, v64
	v_cvt_pk_bf16_f32 v64, v194, v195
	v_cvt_pk_bf16_f32 v65, v196, v197
	v_cvt_pk_bf16_f32 v66, v198, v199
	v_cvt_pk_bf16_f32 v67, v200, v201
	v_cvt_pk_bf16_f32 v68, v202, v203
	v_cvt_pk_bf16_f32 v69, v204, v205
	v_cvt_pk_bf16_f32 v70, v206, v207
	v_cvt_pk_bf16_f32 v71, v208, v209
	v_cvt_pk_bf16_f32 v72, v210, v211
	v_cvt_pk_bf16_f32 v73, v212, v213
	v_cvt_pk_bf16_f32 v74, v214, v215
	v_cvt_pk_bf16_f32 v75, v216, v217
	v_cvt_pk_bf16_f32 v76, v218, v219
	v_cvt_pk_bf16_f32 v77, v220, v221
	v_cvt_pk_bf16_f32 v78, v222, v223
	v_cvt_pk_bf16_f32 v79, v224, v225
	ds_read_b128 v[80:83], v243 offset:39424
	ds_read_b128 v[84:87], v243 offset:39456
	ds_read_b128 v[88:91], v243 offset:39488
	ds_read_b128 v[92:95], v243 offset:39520
	s_setprio 1
	s_waitcnt lgkmcnt(0)
	v_mfma_f32_32x32x16_bf16 v[48:63], v[128:131], v[64:67], v[48:63]
	v_mfma_f32_32x32x16_bf16 v[48:63], v[132:135], v[68:71], v[48:63]
	v_mfma_f32_32x32x16_bf16 v[48:63], v[136:139], v[72:75], v[48:63]
	v_mfma_f32_32x32x16_bf16 v[48:63], v[140:143], v[76:79], v[48:63]
	ds_read_b128 v[128:131], v243 offset:44032
	ds_read_b128 v[132:135], v243 offset:44064
	ds_read_b128 v[136:139], v243 offset:44096
	ds_read_b128 v[140:143], v243 offset:44128
	v_mfma_f32_32x32x16_bf16 v[32:47], v[80:83], v[64:67], v[32:47]
	v_mfma_f32_32x32x16_bf16 v[32:47], v[84:87], v[68:71], v[32:47]
	v_mfma_f32_32x32x16_bf16 v[32:47], v[88:91], v[72:75], v[32:47]
	v_mfma_f32_32x32x16_bf16 v[32:47], v[92:95], v[76:79], v[32:47]
	ds_read_b128 v[80:83], v243 offset:48640
	ds_read_b128 v[84:87], v243 offset:48672
	ds_read_b128 v[88:91], v243 offset:48704
	ds_read_b128 v[92:95], v243 offset:48736
	s_waitcnt lgkmcnt(0)
	v_mfma_f32_32x32x16_bf16 v[16:31], v[128:131], v[64:67], v[16:31]
	v_mfma_f32_32x32x16_bf16 v[0:15], v[80:83], v[64:67], v[0:15]
	v_mfma_f32_32x32x16_bf16 v[16:31], v[132:135], v[68:71], v[16:31]
	v_mfma_f32_32x32x16_bf16 v[0:15], v[84:87], v[68:71], v[0:15]
	v_mfma_f32_32x32x16_bf16 v[16:31], v[136:139], v[72:75], v[16:31]
	v_mfma_f32_32x32x16_bf16 v[0:15], v[88:91], v[72:75], v[0:15]
	v_mfma_f32_32x32x16_bf16 v[16:31], v[140:143], v[76:79], v[16:31]
	v_mfma_f32_32x32x16_bf16 v[0:15], v[92:95], v[76:79], v[0:15]
	s_setprio 0
	v_add_f32_e32 v128, v194, v198
	v_add_f32_e32 v129, v195, v199
	v_add_f32_e32 v130, v196, v200
	v_add_f32_e32 v131, v197, v201
	v_add_f32_e32 v128, v128, v202
	v_add_f32_e32 v129, v129, v203
	v_add_f32_e32 v130, v130, v204
	v_add_f32_e32 v131, v131, v205
	v_add_f32_e32 v128, v128, v206
	v_add_f32_e32 v129, v129, v207
	v_add_f32_e32 v130, v130, v208
	v_add_f32_e32 v131, v131, v209
	v_add_f32_e32 v128, v128, v210
	v_add_f32_e32 v129, v129, v211
	v_add_f32_e32 v130, v130, v212
	v_add_f32_e32 v131, v131, v213
	v_add_f32_e32 v128, v128, v214
	v_add_f32_e32 v129, v129, v215
	v_add_f32_e32 v130, v130, v216
	v_add_f32_e32 v131, v131, v217
	v_add_f32_e32 v128, v128, v218
	v_add_f32_e32 v129, v129, v219
	v_add_f32_e32 v130, v130, v220
	v_add_f32_e32 v131, v131, v221
	v_add_f32_e32 v128, v128, v222
	v_add_f32_e32 v129, v129, v223
	v_add_f32_e32 v130, v130, v224
	v_add_f32_e32 v131, v131, v225
	v_add_f32_e32 v128, v128, v129
	v_add_f32_e32 v130, v130, v131
	v_add_f32_e32 v128, v128, v130
	v_add_f32_e32 v248, v248, v128
	v_add_u32_e32 v64, 0xd000, v240
	s_cmp_eq_u64 s[0:1], 0
	s_cbranch_scc1 .La2_n0v_a
	s_waitcnt vmcnt(4)
	s_branch .La2_n0v_b

.La2t0_pw:
	s_waitcnt lgkmcnt(0)
	s_barrier
	s_cmp_ge_u32 s22, s62
	s_cbranch_scc1 .LBB0_631
.LBB0_631:
	s_setprio 1
	ds_read_b128 v[140:143], v247
	ds_read_b128 v[136:139], v247 offset:32
	ds_read_b128 v[132:135], v247 offset:64
	ds_read_b128 v[128:131], v247 offset:96
	ds_read_b128 v[172:175], v246 offset:17408
	ds_read_b128 v[168:171], v246 offset:17440
	ds_read_b128 v[164:167], v246 offset:17472
	ds_read_b128 v[160:163], v246 offset:17504
	ds_read_b128 v[156:159], v246 offset:26112
	ds_read_b128 v[152:155], v246 offset:26144
	ds_read_b128 v[148:151], v246 offset:26176
	ds_read_b128 v[144:147], v246 offset:26208
	s_cmp_lt_u32 s42, s69
	s_cselect_b64 s[40:41], -1, 0
	s_cmpk_gt_i32 s47, 0xff01
	s_cselect_b64 s[70:71], -1, 0
	s_and_b64 s[70:71], s[40:41], s[70:71]
	s_and_b64 vcc, exec, s[70:71]
	s_cbranch_vccnz .LBB0_633
	s_and_b64 s[40:41], s[40:41], exec
	s_cselect_b32 s40, 0, 0x400
	s_add_i32 s40, s63, s40
	v_mov_b32_e32 v64, s40
	ds_read_b32 v250, v64
	s_cmp_eq_u64 s[0:1], 0
	s_waitcnt lgkmcnt(8)
	v_mfma_f32_32x32x16_bf16 v[64:79], v[172:175], v[140:143], 0
	s_cbranch_scc1 .La2t1_nl0
	v_add_co_u32_e32 v186, vcc, 0xffff8000, v192
	s_nop 1
	v_addc_co_u32_e32 v187, vcc, -1, v193, vcc
	global_load_dwordx4 v[104:107], v[186:187], off
.La2t1_nl0:
	s_waitcnt lgkmcnt(7)
	v_mfma_f32_32x32x16_bf16 v[64:79], v[168:171], v[136:139], v[64:79]
	s_cbranch_scc1 .La2t1_nl1
	global_load_dwordx4 v[108:111], v[192:193], off
.La2t1_nl1:
	s_waitcnt lgkmcnt(6)
	v_mfma_f32_32x32x16_bf16 v[64:79], v[164:167], v[132:135], v[64:79]
	s_cbranch_scc1 .La2t1_nl2
	v_add_co_u32_e32 v186, vcc, 0xffc00000, v190
	s_nop 1
	v_addc_co_u32_e32 v187, vcc, -1, v191, vcc
	global_load_dwordx4 v[112:115], v[186:187], off
.La2t1_nl2:
	s_waitcnt lgkmcnt(5)
	v_mfma_f32_32x32x16_bf16 v[64:79], v[160:163], v[128:131], v[64:79]
	s_cbranch_scc1 .La2t1_nl3
	global_load_dwordx4 v[116:119], v[190:191], off
.La2t1_nl3:
	s_waitcnt lgkmcnt(4)
	v_mfma_f32_32x32x16_bf16 v[80:95], v[156:159], v[140:143], 0
	s_waitcnt lgkmcnt(0)
	s_nop 10
	v_add_f32_e32 v64, v64, v250
	v_add_f32_e32 v65, v65, v250
	v_add_f32_e32 v66, v66, v250
	v_add_f32_e32 v67, v67, v250
	v_add_f32_e32 v68, v68, v250
	v_add_f32_e32 v69, v69, v250
	v_add_f32_e32 v70, v70, v250
	v_add_f32_e32 v71, v71, v250
	v_add_f32_e32 v72, v72, v250
	v_add_f32_e32 v73, v73, v250
	v_mfma_f32_32x32x16_bf16 v[80:95], v[152:155], v[136:139], v[80:95]
	v_add_f32_e32 v74, v74, v250
	v_add_f32_e32 v75, v75, v250
	v_add_f32_e32 v76, v76, v250
	v_add_f32_e32 v77, v77, v250
	v_add_f32_e32 v78, v78, v250
	v_add_f32_e32 v79, v79, v250
	v_exp_f32_e32 v64, v64
	v_exp_f32_e32 v65, v65
	v_exp_f32_e32 v66, v66
	v_exp_f32_e32 v67, v67
	v_mfma_f32_32x32x16_bf16 v[80:95], v[148:151], v[132:135], v[80:95]
	v_exp_f32_e32 v68, v68
	v_exp_f32_e32 v69, v69
	v_exp_f32_e32 v70, v70
	v_exp_f32_e32 v71, v71
	v_exp_f32_e32 v72, v72
	v_exp_f32_e32 v73, v73
	v_exp_f32_e32 v74, v74
	v_exp_f32_e32 v75, v75
	v_exp_f32_e32 v76, v76
	v_exp_f32_e32 v77, v77
	v_mfma_f32_32x32x16_bf16 v[80:95], v[144:147], v[128:131], v[80:95]
	ds_read_b128 v[144:147], v243 offset:53248
	ds_read_b128 v[148:151], v243 offset:53280
	ds_read_b128 v[152:155], v243 offset:57856
	ds_read_b128 v[156:159], v243 offset:57888
	ds_read_b128 v[128:131], v243 offset:62464
	ds_read_b128 v[132:135], v243 offset:62496
	ds_read_b128 v[136:139], v244 offset:13824
	ds_read_b128 v[140:143], v244 offset:13856
	v_exp_f32_e32 v78, v78
	v_exp_f32_e32 v79, v79
	v_cvt_pk_bf16_f32 v160, v64, v65
	v_cvt_pk_bf16_f32 v161, v66, v67
	v_cvt_pk_bf16_f32 v162, v68, v69
	v_cvt_pk_bf16_f32 v163, v70, v71
	v_cvt_pk_bf16_f32 v164, v72, v73
	v_cvt_pk_bf16_f32 v165, v74, v75
	v_cvt_pk_bf16_f32 v166, v76, v77
	v_cvt_pk_bf16_f32 v167, v78, v79
	v_add_f32_e32 v80, v80, v250
	v_add_f32_e32 v81, v81, v250
	v_add_f32_e32 v82, v82, v250
	v_add_f32_e32 v83, v83, v250
	v_add_f32_e32 v84, v84, v250
	v_add_f32_e32 v85, v85, v250
	v_add_f32_e32 v86, v86, v250
	v_add_f32_e32 v87, v87, v250
	v_add_f32_e32 v88, v88, v250
	v_add_f32_e32 v89, v89, v250
	s_waitcnt lgkmcnt(7)
	v_mfma_f32_32x32x16_bf16 v[48:63], v[144:147], v[160:163], v[48:63]
	s_cmp_eq_u64 s[0:1], 0
	s_cbranch_scc1 .La2t1_lv_s
	s_waitcnt vmcnt(4)
	ds_write_b128 v239, v[96:99]
	ds_write_b128 v239, v[100:103] offset:8704
	ds_write2_b64 v241, v[120:121], v[122:123] offset1:2
	ds_write2_b64 v242, v[124:125], v[126:127] offset0:128 offset1:130

.LBB0_633:
	s_cmp_eq_u64 s[0:1], 0
	s_cbranch_scc1 .La2t1_nrl
	v_add_co_u32_e32 v64, vcc, 0xffff8000, v192
	s_nop 1
	v_addc_co_u32_e32 v65, vcc, -1, v193, vcc
	global_load_dwordx4 v[104:107], v[64:65], off
	global_load_dwordx4 v[108:111], v[192:193], off
	v_add_co_u32_e32 v64, vcc, 0xffc00000, v190
	s_nop 1
	v_addc_co_u32_e32 v65, vcc, -1, v191, vcc
	global_load_dwordx4 v[112:115], v[64:65], off
	global_load_dwordx4 v[116:119], v[190:191], off

.LBB0_635:
	s_setprio 0
	s_waitcnt lgkmcnt(0)
	ds_read_b128 v[128:131], v243 offset:53248
	ds_read_b128 v[132:135], v243 offset:53280
	ds_read_b128 v[136:139], v243 offset:53312
	ds_read_b128 v[140:143], v243 offset:53344
	s_nop 2
	v_add_f32_e32 v64, v250, v64
	v_add_f32_e32 v65, v250, v65
	v_add_f32_e32 v66, v250, v66
	v_add_f32_e32 v67, v250, v67
	v_add_f32_e32 v68, v250, v68
	v_add_f32_e32 v69, v250, v69
	v_add_f32_e32 v70, v250, v70
	v_add_f32_e32 v71, v250, v71
	v_add_f32_e32 v72, v250, v72
	v_add_f32_e32 v73, v250, v73
	v_add_f32_e32 v74, v250, v74
	v_add_f32_e32 v75, v250, v75
	v_add_f32_e32 v76, v250, v76
	v_add_f32_e32 v77, v250, v77
	v_add_f32_e32 v78, v250, v78
	v_add_f32_e32 v79, v250, v79
	v_add_f32_e32 v80, v80, v250
	v_add_f32_e32 v81, v81, v250
	v_add_f32_e32 v82, v82, v250
	v_add_f32_e32 v83, v83, v250
	v_add_f32_e32 v84, v84, v250
	v_add_f32_e32 v85, v85, v250
	v_add_f32_e32 v86, v86, v250
	v_add_f32_e32 v87, v87, v250
	v_add_f32_e32 v88, v88, v250
	v_add_f32_e32 v89, v89, v250
	v_add_f32_e32 v90, v90, v250
	v_add_f32_e32 v91, v91, v250
	v_add_f32_e32 v92, v92, v250
	v_add_f32_e32 v93, v93, v250
	v_add_f32_e32 v94, v94, v250
	v_add_f32_e32 v95, v95, v250
	v_exp_f32_e32 v64, v64
	v_exp_f32_e32 v65, v65
	v_exp_f32_e32 v66, v66
	v_exp_f32_e32 v67, v67
	v_exp_f32_e32 v68, v68
	v_exp_f32_e32 v69, v69
	v_exp_f32_e32 v70, v70
	v_exp_f32_e32 v71, v71
	v_exp_f32_e32 v72, v72
	v_exp_f32_e32 v73, v73
	v_exp_f32_e32 v74, v74
	v_exp_f32_e32 v75, v75
	v_exp_f32_e32 v76, v76
	v_exp_f32_e32 v77, v77
	v_exp_f32_e32 v78, v78
	v_exp_f32_e32 v79, v79
	v_exp_f32_e32 v80, v80
	v_exp_f32_e32 v81, v81
	v_exp_f32_e32 v82, v82
	v_exp_f32_e32 v83, v83
	v_exp_f32_e32 v84, v84
	v_exp_f32_e32 v85, v85
	v_exp_f32_e32 v86, v86
	v_exp_f32_e32 v87, v87
	v_exp_f32_e32 v88, v88
	v_exp_f32_e32 v89, v89
	v_exp_f32_e32 v90, v90
	v_exp_f32_e32 v91, v91
	v_exp_f32_e32 v92, v92
	v_exp_f32_e32 v93, v93
	v_exp_f32_e32 v94, v94
	v_exp_f32_e32 v95, v95
	v_cvt_pk_bf16_f32 v144, v64, v65
	v_cvt_pk_bf16_f32 v145, v66, v67
	v_cvt_pk_bf16_f32 v146, v68, v69
	v_cvt_pk_bf16_f32 v147, v70, v71
	v_cvt_pk_bf16_f32 v148, v72, v73
	v_cvt_pk_bf16_f32 v149, v74, v75
	v_cvt_pk_bf16_f32 v150, v76, v77
	v_cvt_pk_bf16_f32 v151, v78, v79
	v_cvt_pk_bf16_f32 v152, v80, v81
	v_cvt_pk_bf16_f32 v153, v82, v83
	v_cvt_pk_bf16_f32 v154, v84, v85
	v_cvt_pk_bf16_f32 v155, v86, v87
	v_cvt_pk_bf16_f32 v156, v88, v89
	v_cvt_pk_bf16_f32 v157, v90, v91
	v_cvt_pk_bf16_f32 v158, v92, v93
	v_cvt_pk_bf16_f32 v159, v94, v95
	ds_read_b128 v[160:163], v243 offset:57856
	ds_read_b128 v[164:167], v243 offset:57888
	ds_read_b128 v[168:171], v243 offset:57920
	ds_read_b128 v[172:175], v243 offset:57952
	s_setprio 1
	s_waitcnt lgkmcnt(0)
	v_mfma_f32_32x32x16_bf16 v[48:63], v[128:131], v[144:147], v[48:63]
	v_mfma_f32_32x32x16_bf16 v[48:63], v[132:135], v[148:151], v[48:63]
	v_mfma_f32_32x32x16_bf16 v[48:63], v[136:139], v[152:155], v[48:63]
	v_mfma_f32_32x32x16_bf16 v[48:63], v[140:143], v[156:159], v[48:63]
	ds_read_b128 v[128:131], v243 offset:62464
	ds_read_b128 v[132:135], v243 offset:62496
	ds_read_b128 v[136:139], v243 offset:62528
	ds_read_b128 v[140:143], v243 offset:62560
	v_mfma_f32_32x32x16_bf16 v[32:47], v[160:163], v[144:147], v[32:47]
	v_mfma_f32_32x32x16_bf16 v[32:47], v[164:167], v[148:151], v[32:47]
	v_mfma_f32_32x32x16_bf16 v[32:47], v[168:171], v[152:155], v[32:47]
	v_mfma_f32_32x32x16_bf16 v[32:47], v[172:175], v[156:159], v[32:47]
	ds_read_b128 v[160:163], v244 offset:13824
	ds_read_b128 v[164:167], v244 offset:13856
	ds_read_b128 v[168:171], v244 offset:13888
	ds_read_b128 v[172:175], v244 offset:13920
	s_waitcnt lgkmcnt(0)
	v_mfma_f32_32x32x16_bf16 v[16:31], v[128:131], v[144:147], v[16:31]
	v_mfma_f32_32x32x16_bf16 v[0:15], v[160:163], v[144:147], v[0:15]
	v_mfma_f32_32x32x16_bf16 v[16:31], v[132:135], v[148:151], v[16:31]
	v_mfma_f32_32x32x16_bf16 v[0:15], v[164:167], v[148:151], v[0:15]
	v_mfma_f32_32x32x16_bf16 v[16:31], v[136:139], v[152:155], v[16:31]
	v_mfma_f32_32x32x16_bf16 v[0:15], v[168:171], v[152:155], v[0:15]
	v_mfma_f32_32x32x16_bf16 v[16:31], v[140:143], v[156:159], v[16:31]
	v_mfma_f32_32x32x16_bf16 v[0:15], v[172:175], v[156:159], v[0:15]
	s_setprio 0
	v_add_f32_e32 v128, v64, v68
	v_add_f32_e32 v129, v65, v69
	v_add_f32_e32 v130, v66, v70
	v_add_f32_e32 v131, v67, v71
	v_add_f32_e32 v128, v128, v72
	v_add_f32_e32 v129, v129, v73
	v_add_f32_e32 v130, v130, v74
	v_add_f32_e32 v131, v131, v75
	v_add_f32_e32 v128, v128, v76
	v_add_f32_e32 v129, v129, v77
	v_add_f32_e32 v130, v130, v78
	v_add_f32_e32 v131, v131, v79
	v_add_f32_e32 v128, v128, v80
	v_add_f32_e32 v129, v129, v81
	v_add_f32_e32 v130, v130, v82
	v_add_f32_e32 v131, v131, v83
	v_add_f32_e32 v128, v128, v84
	v_add_f32_e32 v129, v129, v85
	v_add_f32_e32 v130, v130, v86
	v_add_f32_e32 v131, v131, v87
	v_add_f32_e32 v128, v128, v88
	v_add_f32_e32 v129, v129, v89
	v_add_f32_e32 v130, v130, v90
	v_add_f32_e32 v131, v131, v91
	v_add_f32_e32 v128, v128, v92
	v_add_f32_e32 v129, v129, v93
	v_add_f32_e32 v130, v130, v94
	v_add_f32_e32 v131, v131, v95
	v_add_f32_e32 v128, v128, v129
	v_add_f32_e32 v130, v130, v131
	v_add_f32_e32 v128, v128, v130
	v_add_f32_e32 v248, v248, v128
	s_andn2_b64 vcc, exec, s[0:1]
	s_cbranch_vccnz .LBB0_622
	s_waitcnt vmcnt(4)
	ds_write_b128 v239, v[96:99]
	ds_write_b128 v239, v[100:103] offset:8704
	ds_write2_b64 v241, v[120:121], v[122:123] offset1:2
	ds_write2_b64 v242, v[124:125], v[126:127] offset0:128 offset1:130
	s_branch .LBB0_622
